# K-loops: s_setprio 0 and the post-MFMA scalar/address ops moved after the phase barrier (MFMA group reaches the barrier sooner)
# speedup vs baseline: 1.0087x; 1.0087x over previous
.LBB0_57:
	s_add_u32 s22, s0, 0xfffc0080
	s_addc_u32 s23, s1, -1
	s_add_i32 s65, 0, 0x10000
	v_add_u32_e32 v142, s65, v178
	ds_read_b128 v[130:133], v142
	ds_read_b128 v[134:137], v142 offset:1024
	ds_read_b128 v[138:141], v142 offset:2048
	ds_read_b128 v[142:145], v142 offset:3072
	s_cmp_eq_u32 s64, 12
	s_cselect_b32 s49, s37, s23
	s_cselect_b32 s48, s60, s22
	s_cselect_b32 s23, s35, s63
	s_cselect_b32 s22, s61, s62
	v_lshl_add_u64 v[186:187], s[0:1], 0, v[168:169]
	s_add_i32 m0, s47, 0xc000
	ds_read_b128 v[172:175], v180
	ds_read_b128 v[182:185], v180 offset:1024
	ds_read_b128 v[206:209], v180 offset:2048
	ds_read_b128 v[210:213], v180 offset:3072
	ds_read_b128 v[214:217], v180 offset:4096
	ds_read_b128 v[218:221], v180 offset:5120
	ds_read_b128 v[222:225], v180 offset:6144
	ds_read_b128 v[226:229], v180 offset:7168
	global_load_lds_dwordx4 v[186:187], off
	v_lshl_add_u64 v[186:187], s[0:1], 0, v[170:171]
	s_add_i32 m0, s47, 0xe000
	s_nop 0
	global_load_lds_dwordx4 v[186:187], off
	s_waitcnt lgkmcnt(8)
	s_barrier
	s_waitcnt lgkmcnt(0)
	s_setprio 1
	v_mfma_f32_16x16x32_bf16 v[126:129], v[130:133], v[172:175], v[126:129]
	v_mfma_f32_16x16x32_bf16 v[122:125], v[138:141], v[172:175], v[122:125]
	v_mfma_f32_16x16x32_bf16 v[114:117], v[130:133], v[206:209], v[114:117]
	v_mfma_f32_16x16x32_bf16 v[106:109], v[138:141], v[206:209], v[106:109]
	v_mfma_f32_16x16x32_bf16 v[98:101], v[130:133], v[214:217], v[98:101]
	v_mfma_f32_16x16x32_bf16 v[90:93], v[138:141], v[214:217], v[90:93]
	v_mfma_f32_16x16x32_bf16 v[82:85], v[130:133], v[222:225], v[82:85]
	v_mfma_f32_16x16x32_bf16 v[74:77], v[138:141], v[222:225], v[74:77]
	v_mfma_f32_16x16x32_bf16 v[126:129], v[134:137], v[182:185], v[126:129]
	v_mfma_f32_16x16x32_bf16 v[122:125], v[142:145], v[182:185], v[122:125]
	v_mfma_f32_16x16x32_bf16 v[114:117], v[134:137], v[210:213], v[114:117]
	v_mfma_f32_16x16x32_bf16 v[106:109], v[142:145], v[210:213], v[106:109]
	v_mfma_f32_16x16x32_bf16 v[98:101], v[134:137], v[218:221], v[98:101]
	v_mfma_f32_16x16x32_bf16 v[90:93], v[142:145], v[218:221], v[90:93]
	v_mfma_f32_16x16x32_bf16 v[82:85], v[134:137], v[226:229], v[82:85]
	v_mfma_f32_16x16x32_bf16 v[74:77], v[142:145], v[226:229], v[74:77]
	s_barrier
	s_setprio 0
	s_add_i32 s68, 0, 0x14000
	s_add_i32 s65, s65, s27
	v_add_u32_e32 v181, s68, v178
	v_lshl_add_u64 v[186:187], s[22:23], 0, v[0:1]
	s_mov_b32 m0, s65
	ds_read_b128 v[230:233], v181
	ds_read_b128 v[234:237], v181 offset:1024
	ds_read_b128 v[238:241], v181 offset:2048
	ds_read_b128 v[242:245], v181 offset:3072
	global_load_lds_dwordx4 v[186:187], off
	v_lshl_add_u64 v[246:247], s[22:23], 0, v[166:167]
	s_add_i32 m0, s65, 0x2000
	s_nop 0
	global_load_lds_dwordx4 v[246:247], off
	s_barrier
	s_waitcnt lgkmcnt(0)
	s_setprio 1
	v_mfma_f32_16x16x32_bf16 v[118:121], v[230:233], v[172:175], v[118:121]
	v_mfma_f32_16x16x32_bf16 v[110:113], v[238:241], v[172:175], v[110:113]
	v_mfma_f32_16x16x32_bf16 v[102:105], v[230:233], v[206:209], v[102:105]
	v_mfma_f32_16x16x32_bf16 v[94:97], v[238:241], v[206:209], v[94:97]
	v_mfma_f32_16x16x32_bf16 v[86:89], v[230:233], v[214:217], v[86:89]
	v_mfma_f32_16x16x32_bf16 v[78:81], v[238:241], v[214:217], v[78:81]
	v_mfma_f32_16x16x32_bf16 v[70:73], v[230:233], v[222:225], v[70:73]
	v_mfma_f32_16x16x32_bf16 v[66:69], v[238:241], v[222:225], v[66:69]
	v_mfma_f32_16x16x32_bf16 v[118:121], v[234:237], v[182:185], v[118:121]
	v_mfma_f32_16x16x32_bf16 v[110:113], v[242:245], v[182:185], v[110:113]
	v_mfma_f32_16x16x32_bf16 v[102:105], v[234:237], v[210:213], v[102:105]
	v_mfma_f32_16x16x32_bf16 v[94:97], v[242:245], v[210:213], v[94:97]
	v_mfma_f32_16x16x32_bf16 v[86:89], v[234:237], v[218:221], v[86:89]
	v_mfma_f32_16x16x32_bf16 v[78:81], v[242:245], v[218:221], v[78:81]
	v_mfma_f32_16x16x32_bf16 v[70:73], v[234:237], v[226:229], v[70:73]
	v_mfma_f32_16x16x32_bf16 v[66:69], v[242:245], v[226:229], v[66:69]
	s_barrier
	s_setprio 0
	s_mov_b32 m0, s47
	v_lshl_add_u64 v[248:249], s[48:49], 0, v[162:163]
	ds_read_b128 v[172:175], v180 offset:16384
	ds_read_b128 v[182:185], v180 offset:17408
	ds_read_b128 v[206:209], v180 offset:18432
	ds_read_b128 v[210:213], v180 offset:19456
	ds_read_b128 v[214:217], v180 offset:20480
	ds_read_b128 v[218:221], v180 offset:21504
	ds_read_b128 v[222:225], v180 offset:22528
	ds_read_b128 v[226:229], v180 offset:23552
	global_load_lds_dwordx4 v[248:249], off
	v_lshl_add_u64 v[250:251], s[48:49], 0, v[164:165]
	s_mov_b32 m0, s50
	s_nop 0
	global_load_lds_dwordx4 v[250:251], off
	s_barrier
	s_waitcnt lgkmcnt(0)
	s_setprio 1
	v_mfma_f32_16x16x32_bf16 v[62:65], v[130:133], v[172:175], v[62:65]
	v_mfma_f32_16x16x32_bf16 v[58:61], v[138:141], v[172:175], v[58:61]
	v_mfma_f32_16x16x32_bf16 v[50:53], v[130:133], v[206:209], v[50:53]
	v_mfma_f32_16x16x32_bf16 v[42:45], v[138:141], v[206:209], v[42:45]
	v_mfma_f32_16x16x32_bf16 v[34:37], v[130:133], v[214:217], v[34:37]
	v_mfma_f32_16x16x32_bf16 v[26:29], v[138:141], v[214:217], v[26:29]
	v_mfma_f32_16x16x32_bf16 v[18:21], v[130:133], v[222:225], v[18:21]
	v_mfma_f32_16x16x32_bf16 v[10:13], v[138:141], v[222:225], v[10:13]
	v_mfma_f32_16x16x32_bf16 v[62:65], v[134:137], v[182:185], v[62:65]
	v_mfma_f32_16x16x32_bf16 v[58:61], v[142:145], v[182:185], v[58:61]
	v_mfma_f32_16x16x32_bf16 v[50:53], v[134:137], v[210:213], v[50:53]
	v_mfma_f32_16x16x32_bf16 v[42:45], v[142:145], v[210:213], v[42:45]
	v_mfma_f32_16x16x32_bf16 v[34:37], v[134:137], v[218:221], v[34:37]
	v_mfma_f32_16x16x32_bf16 v[26:29], v[142:145], v[218:221], v[26:29]
	v_mfma_f32_16x16x32_bf16 v[18:21], v[134:137], v[226:229], v[18:21]
	v_mfma_f32_16x16x32_bf16 v[10:13], v[142:145], v[226:229], v[10:13]
	s_barrier
	s_setprio 0
	s_add_u32 s66, s22, 0x40000
	s_addc_u32 s67, s23, 0
	s_add_i32 s65, s68, s27
	v_lshl_add_u64 v[130:131], s[66:67], 0, v[0:1]
	s_mov_b32 m0, s65
	s_nop 0
	global_load_lds_dwordx4 v[130:131], off
	v_lshl_add_u64 v[130:131], s[66:67], 0, v[166:167]
	s_add_i32 m0, s65, 0x2000
	s_nop 0
	global_load_lds_dwordx4 v[130:131], off
	s_waitcnt vmcnt(6)
	s_barrier
	s_setprio 1
	v_mfma_f32_16x16x32_bf16 v[54:57], v[230:233], v[172:175], v[54:57]
	v_mfma_f32_16x16x32_bf16 v[46:49], v[238:241], v[172:175], v[46:49]
	v_mfma_f32_16x16x32_bf16 v[38:41], v[230:233], v[206:209], v[38:41]
	v_mfma_f32_16x16x32_bf16 v[30:33], v[238:241], v[206:209], v[30:33]
	v_mfma_f32_16x16x32_bf16 v[22:25], v[230:233], v[214:217], v[22:25]
	v_mfma_f32_16x16x32_bf16 v[14:17], v[238:241], v[214:217], v[14:17]
	v_mfma_f32_16x16x32_bf16 v[6:9], v[230:233], v[222:225], v[6:9]
	v_mfma_f32_16x16x32_bf16 v[2:5], v[238:241], v[222:225], v[2:5]
	v_mfma_f32_16x16x32_bf16 v[54:57], v[234:237], v[182:185], v[54:57]
	v_mfma_f32_16x16x32_bf16 v[46:49], v[242:245], v[182:185], v[46:49]
	v_mfma_f32_16x16x32_bf16 v[38:41], v[234:237], v[210:213], v[38:41]
	v_mfma_f32_16x16x32_bf16 v[30:33], v[242:245], v[210:213], v[30:33]
	v_mfma_f32_16x16x32_bf16 v[22:25], v[234:237], v[218:221], v[22:25]
	v_mfma_f32_16x16x32_bf16 v[14:17], v[242:245], v[218:221], v[14:17]
	v_mfma_f32_16x16x32_bf16 v[6:9], v[234:237], v[226:229], v[6:9]
	v_mfma_f32_16x16x32_bf16 v[2:5], v[242:245], v[226:229], v[2:5]
	s_barrier
	s_setprio 0
	s_add_i32 s65, 0, 0x18000
	v_add_u32_e32 v142, s65, v178
	ds_read_b128 v[130:133], v142
	ds_read_b128 v[134:137], v142 offset:1024
	ds_read_b128 v[138:141], v142 offset:2048
	ds_read_b128 v[142:145], v142 offset:3072
	s_add_u32 s48, s48, 0x40000
	s_addc_u32 s49, s49, 0
	s_mov_b32 m0, s51
	v_lshl_add_u64 v[230:231], s[48:49], 0, v[162:163]
	ds_read_b128 v[172:175], v180 offset:32768
	ds_read_b128 v[182:185], v180 offset:33792
	ds_read_b128 v[206:209], v180 offset:34816
	ds_read_b128 v[210:213], v180 offset:35840
	ds_read_b128 v[214:217], v180 offset:36864
	ds_read_b128 v[218:221], v180 offset:37888
	ds_read_b128 v[222:225], v180 offset:38912
	ds_read_b128 v[226:229], v180 offset:39936
	global_load_lds_dwordx4 v[230:231], off
	v_lshl_add_u64 v[230:231], s[48:49], 0, v[164:165]
	s_mov_b32 m0, s54
	s_nop 0
	global_load_lds_dwordx4 v[230:231], off
	s_waitcnt lgkmcnt(8)
	s_barrier
	s_waitcnt lgkmcnt(0)
	s_setprio 1
	v_mfma_f32_16x16x32_bf16 v[126:129], v[130:133], v[172:175], v[126:129]
	v_mfma_f32_16x16x32_bf16 v[122:125], v[138:141], v[172:175], v[122:125]
	v_mfma_f32_16x16x32_bf16 v[114:117], v[130:133], v[206:209], v[114:117]
	v_mfma_f32_16x16x32_bf16 v[106:109], v[138:141], v[206:209], v[106:109]
	v_mfma_f32_16x16x32_bf16 v[98:101], v[130:133], v[214:217], v[98:101]
	v_mfma_f32_16x16x32_bf16 v[90:93], v[138:141], v[214:217], v[90:93]
	v_mfma_f32_16x16x32_bf16 v[82:85], v[130:133], v[222:225], v[82:85]
	v_mfma_f32_16x16x32_bf16 v[74:77], v[138:141], v[222:225], v[74:77]
	v_mfma_f32_16x16x32_bf16 v[126:129], v[134:137], v[182:185], v[126:129]
	v_mfma_f32_16x16x32_bf16 v[122:125], v[142:145], v[182:185], v[122:125]
	v_mfma_f32_16x16x32_bf16 v[114:117], v[134:137], v[210:213], v[114:117]
	v_mfma_f32_16x16x32_bf16 v[106:109], v[142:145], v[210:213], v[106:109]
	v_mfma_f32_16x16x32_bf16 v[98:101], v[134:137], v[218:221], v[98:101]
	v_mfma_f32_16x16x32_bf16 v[90:93], v[142:145], v[218:221], v[90:93]
	v_mfma_f32_16x16x32_bf16 v[82:85], v[134:137], v[226:229], v[82:85]
	v_mfma_f32_16x16x32_bf16 v[74:77], v[142:145], v[226:229], v[74:77]
	s_barrier
	s_setprio 0
	s_add_i32 s48, 0, 0x1c000
	s_add_i32 s49, s65, s27
	v_add_u32_e32 v181, s48, v178
	v_lshl_add_u64 v[186:187], v[186:187], 0, s[94:95]
	s_mov_b32 m0, s49
	ds_read_b128 v[230:233], v181
	ds_read_b128 v[234:237], v181 offset:1024
	ds_read_b128 v[238:241], v181 offset:2048
	ds_read_b128 v[242:245], v181 offset:3072
	global_load_lds_dwordx4 v[186:187], off
	v_lshl_add_u64 v[186:187], v[246:247], 0, s[94:95]
	s_add_i32 m0, s49, 0x2000
	s_nop 0
	global_load_lds_dwordx4 v[186:187], off
	s_barrier
	s_waitcnt lgkmcnt(0)
	s_setprio 1
	v_mfma_f32_16x16x32_bf16 v[118:121], v[230:233], v[172:175], v[118:121]
	v_mfma_f32_16x16x32_bf16 v[110:113], v[238:241], v[172:175], v[110:113]
	v_mfma_f32_16x16x32_bf16 v[102:105], v[230:233], v[206:209], v[102:105]
	v_mfma_f32_16x16x32_bf16 v[94:97], v[238:241], v[206:209], v[94:97]
	v_mfma_f32_16x16x32_bf16 v[86:89], v[230:233], v[214:217], v[86:89]
	v_mfma_f32_16x16x32_bf16 v[78:81], v[238:241], v[214:217], v[78:81]
	v_mfma_f32_16x16x32_bf16 v[70:73], v[230:233], v[222:225], v[70:73]
	v_mfma_f32_16x16x32_bf16 v[66:69], v[238:241], v[222:225], v[66:69]
	v_mfma_f32_16x16x32_bf16 v[118:121], v[234:237], v[182:185], v[118:121]
	v_mfma_f32_16x16x32_bf16 v[110:113], v[242:245], v[182:185], v[110:113]
	v_mfma_f32_16x16x32_bf16 v[102:105], v[234:237], v[210:213], v[102:105]
	v_mfma_f32_16x16x32_bf16 v[94:97], v[242:245], v[210:213], v[94:97]
	v_mfma_f32_16x16x32_bf16 v[86:89], v[234:237], v[218:221], v[86:89]
	v_mfma_f32_16x16x32_bf16 v[78:81], v[242:245], v[218:221], v[78:81]
	v_mfma_f32_16x16x32_bf16 v[70:73], v[234:237], v[226:229], v[70:73]
	v_mfma_f32_16x16x32_bf16 v[66:69], v[242:245], v[226:229], v[66:69]
	s_barrier
	s_setprio 0
	s_mov_b32 m0, s55
	v_lshl_add_u64 v[186:187], v[248:249], 0, s[94:95]
	ds_read_b128 v[172:175], v180 offset:49152
	ds_read_b128 v[182:185], v180 offset:50176
	ds_read_b128 v[206:209], v180 offset:51200
	ds_read_b128 v[210:213], v180 offset:52224
	ds_read_b128 v[214:217], v180 offset:53248
	ds_read_b128 v[218:221], v180 offset:54272
	ds_read_b128 v[222:225], v180 offset:55296
	ds_read_b128 v[226:229], v180 offset:56320
	global_load_lds_dwordx4 v[186:187], off
	v_lshl_add_u64 v[186:187], v[250:251], 0, s[94:95]
	s_mov_b32 m0, s56
	s_nop 0
	global_load_lds_dwordx4 v[186:187], off
	s_barrier
	s_waitcnt lgkmcnt(0)
	s_setprio 1
	v_mfma_f32_16x16x32_bf16 v[62:65], v[130:133], v[172:175], v[62:65]
	v_mfma_f32_16x16x32_bf16 v[58:61], v[138:141], v[172:175], v[58:61]
	v_mfma_f32_16x16x32_bf16 v[50:53], v[130:133], v[206:209], v[50:53]
	v_mfma_f32_16x16x32_bf16 v[42:45], v[138:141], v[206:209], v[42:45]
	v_mfma_f32_16x16x32_bf16 v[34:37], v[130:133], v[214:217], v[34:37]
	v_mfma_f32_16x16x32_bf16 v[26:29], v[138:141], v[214:217], v[26:29]
	v_mfma_f32_16x16x32_bf16 v[18:21], v[130:133], v[222:225], v[18:21]
	v_mfma_f32_16x16x32_bf16 v[10:13], v[138:141], v[222:225], v[10:13]
	v_mfma_f32_16x16x32_bf16 v[62:65], v[134:137], v[182:185], v[62:65]
	v_mfma_f32_16x16x32_bf16 v[58:61], v[142:145], v[182:185], v[58:61]
	v_mfma_f32_16x16x32_bf16 v[50:53], v[134:137], v[210:213], v[50:53]
	v_mfma_f32_16x16x32_bf16 v[42:45], v[142:145], v[210:213], v[42:45]
	v_mfma_f32_16x16x32_bf16 v[34:37], v[134:137], v[218:221], v[34:37]
	v_mfma_f32_16x16x32_bf16 v[26:29], v[142:145], v[218:221], v[26:29]
	v_mfma_f32_16x16x32_bf16 v[18:21], v[134:137], v[226:229], v[18:21]
	v_mfma_f32_16x16x32_bf16 v[10:13], v[142:145], v[226:229], v[10:13]
	s_barrier
	s_setprio 0
	s_add_u32 s22, s22, 0x40080
	s_addc_u32 s23, s23, 0
	s_add_i32 s48, s48, s27
	v_lshl_add_u64 v[130:131], s[22:23], 0, v[0:1]
	s_mov_b32 m0, s48
	s_nop 0
	global_load_lds_dwordx4 v[130:131], off
	v_lshl_add_u64 v[130:131], s[22:23], 0, v[166:167]
	s_add_i32 m0, s48, 0x2000
	s_nop 0
	global_load_lds_dwordx4 v[130:131], off
	s_waitcnt vmcnt(6)
	s_barrier
	s_setprio 1
	v_mfma_f32_16x16x32_bf16 v[54:57], v[230:233], v[172:175], v[54:57]
	v_mfma_f32_16x16x32_bf16 v[46:49], v[238:241], v[172:175], v[46:49]
	v_mfma_f32_16x16x32_bf16 v[38:41], v[230:233], v[206:209], v[38:41]
	v_mfma_f32_16x16x32_bf16 v[30:33], v[238:241], v[206:209], v[30:33]
	v_mfma_f32_16x16x32_bf16 v[22:25], v[230:233], v[214:217], v[22:25]
	v_mfma_f32_16x16x32_bf16 v[14:17], v[238:241], v[214:217], v[14:17]
	v_mfma_f32_16x16x32_bf16 v[6:9], v[230:233], v[222:225], v[6:9]
	v_mfma_f32_16x16x32_bf16 v[2:5], v[238:241], v[222:225], v[2:5]
	v_mfma_f32_16x16x32_bf16 v[54:57], v[234:237], v[182:185], v[54:57]
	v_mfma_f32_16x16x32_bf16 v[46:49], v[242:245], v[182:185], v[46:49]
	v_mfma_f32_16x16x32_bf16 v[38:41], v[234:237], v[210:213], v[38:41]
	v_mfma_f32_16x16x32_bf16 v[30:33], v[242:245], v[210:213], v[30:33]
	v_mfma_f32_16x16x32_bf16 v[22:25], v[234:237], v[218:221], v[22:25]
	v_mfma_f32_16x16x32_bf16 v[14:17], v[242:245], v[218:221], v[14:17]
	v_mfma_f32_16x16x32_bf16 v[6:9], v[234:237], v[226:229], v[6:9]
	v_mfma_f32_16x16x32_bf16 v[2:5], v[242:245], v[226:229], v[2:5]
	s_barrier
	s_setprio 0
	s_add_i32 s64, s64, 2
	s_add_u32 s0, s0, 0x100
	s_addc_u32 s1, s1, 0
	s_add_u32 s62, s62, 0x100
	s_addc_u32 s63, s63, 0
	s_cmp_gt_u32 s64, 13
	s_cbranch_scc0 .LBB0_57
	v_lshl_or_b32 v172, s59, 8, v179
	v_ashrrev_i32_e32 v173, 31, v172
	v_cndmask_b32_e64 v131, 0, 1, s[2:3]
	v_lshl_add_u64 v[174:175], v[172:173], 2, s[8:9]
	v_mov_b32_e32 v130, 0
	v_cmp_ne_u32_e64 s[0:1], 1, v131
	s_andn2_b64 vcc, exec, s[2:3]
	v_mov_b32_e32 v134, 0
	v_mov_b32_e32 v135, 0
	v_mov_b32_e32 v136, 0
	v_mov_b32_e32 v137, 0
	s_cbranch_vccnz .LBB0_60
	global_load_dwordx4 v[134:137], v[174:175], off

.LBB0_95:
	s_add_u32 s22, s8, 0xfffc0080
	s_addc_u32 s23, s9, -1
	s_add_i32 s63, 0, 0x10000
	v_add_u32_e32 v78, s63, v178
	ds_read_b128 v[58:61], v78
	ds_read_b128 v[66:69], v78 offset:1024
	ds_read_b128 v[74:77], v78 offset:2048
	ds_read_b128 v[78:81], v78 offset:3072
	s_cmp_eq_u32 s49, 12
	s_cselect_b32 s29, s25, s23
	s_cselect_b32 s28, s26, s22
	s_cselect_b32 s23, s27, s47
	s_cselect_b32 s22, s30, s31
	v_lshl_add_u64 v[186:187], s[8:9], 0, v[168:169]
	s_add_i32 m0, s3, 0xc000
	ds_read_b128 v[172:175], v180
	ds_read_b128 v[182:185], v180 offset:1024
	ds_read_b128 v[206:209], v180 offset:2048
	ds_read_b128 v[210:213], v180 offset:3072
	ds_read_b128 v[214:217], v180 offset:4096
	ds_read_b128 v[218:221], v180 offset:5120
	ds_read_b128 v[222:225], v180 offset:6144
	ds_read_b128 v[226:229], v180 offset:7168
	global_load_lds_dwordx4 v[186:187], off
	v_lshl_add_u64 v[186:187], s[8:9], 0, v[170:171]
	s_add_i32 m0, s3, 0xe000
	s_nop 0
	global_load_lds_dwordx4 v[186:187], off
	s_waitcnt lgkmcnt(8)
	s_barrier
	s_waitcnt lgkmcnt(0)
	s_setprio 1
	v_mfma_f32_16x16x32_bf16 v[142:145], v[58:61], v[172:175], v[142:145]
	v_mfma_f32_16x16x32_bf16 v[138:141], v[74:77], v[172:175], v[138:141]
	v_mfma_f32_16x16x32_bf16 v[126:129], v[58:61], v[206:209], v[126:129]
	v_mfma_f32_16x16x32_bf16 v[118:121], v[74:77], v[206:209], v[118:121]
	v_mfma_f32_16x16x32_bf16 v[110:113], v[58:61], v[214:217], v[110:113]
	v_mfma_f32_16x16x32_bf16 v[102:105], v[74:77], v[214:217], v[102:105]
	v_mfma_f32_16x16x32_bf16 v[94:97], v[58:61], v[222:225], v[94:97]
	v_mfma_f32_16x16x32_bf16 v[86:89], v[74:77], v[222:225], v[86:89]
	v_mfma_f32_16x16x32_bf16 v[142:145], v[66:69], v[182:185], v[142:145]
	v_mfma_f32_16x16x32_bf16 v[138:141], v[78:81], v[182:185], v[138:141]
	v_mfma_f32_16x16x32_bf16 v[126:129], v[66:69], v[210:213], v[126:129]
	v_mfma_f32_16x16x32_bf16 v[118:121], v[78:81], v[210:213], v[118:121]
	v_mfma_f32_16x16x32_bf16 v[110:113], v[66:69], v[218:221], v[110:113]
	v_mfma_f32_16x16x32_bf16 v[102:105], v[78:81], v[218:221], v[102:105]
	v_mfma_f32_16x16x32_bf16 v[94:97], v[66:69], v[226:229], v[94:97]
	v_mfma_f32_16x16x32_bf16 v[86:89], v[78:81], v[226:229], v[86:89]
	s_barrier
	s_setprio 0
	s_add_i32 s66, 0, 0x14000
	s_add_i32 s63, s63, s37
	v_add_u32_e32 v181, s66, v178
	v_lshl_add_u64 v[186:187], s[22:23], 0, v[0:1]
	s_mov_b32 m0, s63
	ds_read_b128 v[230:233], v181
	ds_read_b128 v[234:237], v181 offset:1024
	ds_read_b128 v[238:241], v181 offset:2048
	ds_read_b128 v[242:245], v181 offset:3072
	global_load_lds_dwordx4 v[186:187], off
	v_lshl_add_u64 v[246:247], s[22:23], 0, v[166:167]
	s_add_i32 m0, s63, 0x2000
	s_nop 0
	global_load_lds_dwordx4 v[246:247], off
	s_barrier
	s_waitcnt lgkmcnt(0)
	s_setprio 1
	v_mfma_f32_16x16x32_bf16 v[134:137], v[230:233], v[172:175], v[134:137]
	v_mfma_f32_16x16x32_bf16 v[130:133], v[238:241], v[172:175], v[130:133]
	v_mfma_f32_16x16x32_bf16 v[122:125], v[230:233], v[206:209], v[122:125]
	v_mfma_f32_16x16x32_bf16 v[114:117], v[238:241], v[206:209], v[114:117]
	v_mfma_f32_16x16x32_bf16 v[106:109], v[230:233], v[214:217], v[106:109]
	v_mfma_f32_16x16x32_bf16 v[98:101], v[238:241], v[214:217], v[98:101]
	v_mfma_f32_16x16x32_bf16 v[90:93], v[230:233], v[222:225], v[90:93]
	v_mfma_f32_16x16x32_bf16 v[82:85], v[238:241], v[222:225], v[82:85]
	v_mfma_f32_16x16x32_bf16 v[134:137], v[234:237], v[182:185], v[134:137]
	v_mfma_f32_16x16x32_bf16 v[130:133], v[242:245], v[182:185], v[130:133]
	v_mfma_f32_16x16x32_bf16 v[122:125], v[234:237], v[210:213], v[122:125]
	v_mfma_f32_16x16x32_bf16 v[114:117], v[242:245], v[210:213], v[114:117]
	v_mfma_f32_16x16x32_bf16 v[106:109], v[234:237], v[218:221], v[106:109]
	v_mfma_f32_16x16x32_bf16 v[98:101], v[242:245], v[218:221], v[98:101]
	v_mfma_f32_16x16x32_bf16 v[90:93], v[234:237], v[226:229], v[90:93]
	v_mfma_f32_16x16x32_bf16 v[82:85], v[242:245], v[226:229], v[82:85]
	s_barrier
	s_setprio 0
	s_mov_b32 m0, s3
	v_lshl_add_u64 v[248:249], s[28:29], 0, v[162:163]
	ds_read_b128 v[172:175], v180 offset:16384
	ds_read_b128 v[182:185], v180 offset:17408
	ds_read_b128 v[206:209], v180 offset:18432
	ds_read_b128 v[210:213], v180 offset:19456
	ds_read_b128 v[214:217], v180 offset:20480
	ds_read_b128 v[218:221], v180 offset:21504
	ds_read_b128 v[222:225], v180 offset:22528
	ds_read_b128 v[226:229], v180 offset:23552
	global_load_lds_dwordx4 v[248:249], off
	v_lshl_add_u64 v[250:251], s[28:29], 0, v[164:165]
	s_mov_b32 m0, s56
	s_nop 0
	global_load_lds_dwordx4 v[250:251], off
	s_barrier
	s_waitcnt lgkmcnt(0)
	s_setprio 1
	v_mfma_f32_16x16x32_bf16 v[70:73], v[58:61], v[172:175], v[70:73]
	v_mfma_f32_16x16x32_bf16 v[54:57], v[74:77], v[172:175], v[54:57]
	v_mfma_f32_16x16x32_bf16 v[46:49], v[58:61], v[206:209], v[46:49]
	v_mfma_f32_16x16x32_bf16 v[38:41], v[74:77], v[206:209], v[38:41]
	v_mfma_f32_16x16x32_bf16 v[30:33], v[58:61], v[214:217], v[30:33]
	v_mfma_f32_16x16x32_bf16 v[22:25], v[74:77], v[214:217], v[22:25]
	v_mfma_f32_16x16x32_bf16 v[14:17], v[58:61], v[222:225], v[14:17]
	v_mfma_f32_16x16x32_bf16 v[6:9], v[74:77], v[222:225], v[6:9]
	v_mfma_f32_16x16x32_bf16 v[70:73], v[66:69], v[182:185], v[70:73]
	v_mfma_f32_16x16x32_bf16 v[54:57], v[78:81], v[182:185], v[54:57]
	v_mfma_f32_16x16x32_bf16 v[46:49], v[66:69], v[210:213], v[46:49]
	v_mfma_f32_16x16x32_bf16 v[38:41], v[78:81], v[210:213], v[38:41]
	v_mfma_f32_16x16x32_bf16 v[30:33], v[66:69], v[218:221], v[30:33]
	v_mfma_f32_16x16x32_bf16 v[22:25], v[78:81], v[218:221], v[22:25]
	v_mfma_f32_16x16x32_bf16 v[14:17], v[66:69], v[226:229], v[14:17]
	v_mfma_f32_16x16x32_bf16 v[6:9], v[78:81], v[226:229], v[6:9]
	s_barrier
	s_setprio 0
	s_add_u32 s64, s22, 0x40000
	s_addc_u32 s65, s23, 0
	s_add_i32 s63, s66, s37
	v_lshl_add_u64 v[58:59], s[64:65], 0, v[0:1]
	s_mov_b32 m0, s63
	s_nop 0
	global_load_lds_dwordx4 v[58:59], off
	v_lshl_add_u64 v[58:59], s[64:65], 0, v[166:167]
	s_add_i32 m0, s63, 0x2000
	s_nop 0
	global_load_lds_dwordx4 v[58:59], off
	s_waitcnt vmcnt(6)
	s_barrier
	s_setprio 1
	v_mfma_f32_16x16x32_bf16 v[50:53], v[238:241], v[172:175], v[50:53]
	v_mfma_f32_16x16x32_bf16 v[42:45], v[230:233], v[206:209], v[42:45]
	v_mfma_f32_16x16x32_bf16 v[34:37], v[238:241], v[206:209], v[34:37]
	v_mfma_f32_16x16x32_bf16 v[26:29], v[230:233], v[214:217], v[26:29]
	v_mfma_f32_16x16x32_bf16 v[18:21], v[238:241], v[214:217], v[18:21]
	v_mfma_f32_16x16x32_bf16 v[10:13], v[230:233], v[222:225], v[10:13]
	v_mfma_f32_16x16x32_bf16 v[2:5], v[238:241], v[222:225], v[2:5]
	v_mfma_f32_16x16x32_bf16 v[58:61], v[230:233], v[172:175], v[62:65]
	v_mfma_f32_16x16x32_bf16 v[50:53], v[242:245], v[182:185], v[50:53]
	v_mfma_f32_16x16x32_bf16 v[42:45], v[234:237], v[210:213], v[42:45]
	v_mfma_f32_16x16x32_bf16 v[34:37], v[242:245], v[210:213], v[34:37]
	v_mfma_f32_16x16x32_bf16 v[26:29], v[234:237], v[218:221], v[26:29]
	v_mfma_f32_16x16x32_bf16 v[18:21], v[242:245], v[218:221], v[18:21]
	v_mfma_f32_16x16x32_bf16 v[10:13], v[234:237], v[226:229], v[10:13]
	v_mfma_f32_16x16x32_bf16 v[2:5], v[242:245], v[226:229], v[2:5]
	v_mfma_f32_16x16x32_bf16 v[58:61], v[234:237], v[182:185], v[58:61]
	s_barrier
	s_setprio 0
	s_add_i32 s63, 0, 0x18000
	v_add_u32_e32 v78, s63, v178
	ds_read_b128 v[62:65], v78
	ds_read_b128 v[66:69], v78 offset:1024
	ds_read_b128 v[74:77], v78 offset:2048
	ds_read_b128 v[78:81], v78 offset:3072
	s_add_u32 s28, s28, 0x40000
	s_addc_u32 s29, s29, 0
	s_mov_b32 m0, s57
	v_lshl_add_u64 v[230:231], s[28:29], 0, v[162:163]
	ds_read_b128 v[172:175], v180 offset:32768
	ds_read_b128 v[182:185], v180 offset:33792
	ds_read_b128 v[206:209], v180 offset:34816
	ds_read_b128 v[210:213], v180 offset:35840
	ds_read_b128 v[214:217], v180 offset:36864
	ds_read_b128 v[218:221], v180 offset:37888
	ds_read_b128 v[222:225], v180 offset:38912
	ds_read_b128 v[226:229], v180 offset:39936
	global_load_lds_dwordx4 v[230:231], off
	v_lshl_add_u64 v[230:231], s[28:29], 0, v[164:165]
	s_mov_b32 m0, s58
	s_nop 0
	global_load_lds_dwordx4 v[230:231], off
	s_waitcnt lgkmcnt(8)
	s_barrier
	s_waitcnt lgkmcnt(0)
	s_setprio 1
	v_mfma_f32_16x16x32_bf16 v[142:145], v[62:65], v[172:175], v[142:145]
	v_mfma_f32_16x16x32_bf16 v[138:141], v[74:77], v[172:175], v[138:141]
	v_mfma_f32_16x16x32_bf16 v[126:129], v[62:65], v[206:209], v[126:129]
	v_mfma_f32_16x16x32_bf16 v[118:121], v[74:77], v[206:209], v[118:121]
	v_mfma_f32_16x16x32_bf16 v[110:113], v[62:65], v[214:217], v[110:113]
	v_mfma_f32_16x16x32_bf16 v[102:105], v[74:77], v[214:217], v[102:105]
	v_mfma_f32_16x16x32_bf16 v[94:97], v[62:65], v[222:225], v[94:97]
	v_mfma_f32_16x16x32_bf16 v[86:89], v[74:77], v[222:225], v[86:89]
	v_mfma_f32_16x16x32_bf16 v[142:145], v[66:69], v[182:185], v[142:145]
	v_mfma_f32_16x16x32_bf16 v[138:141], v[78:81], v[182:185], v[138:141]
	v_mfma_f32_16x16x32_bf16 v[126:129], v[66:69], v[210:213], v[126:129]
	v_mfma_f32_16x16x32_bf16 v[118:121], v[78:81], v[210:213], v[118:121]
	v_mfma_f32_16x16x32_bf16 v[110:113], v[66:69], v[218:221], v[110:113]
	v_mfma_f32_16x16x32_bf16 v[102:105], v[78:81], v[218:221], v[102:105]
	v_mfma_f32_16x16x32_bf16 v[94:97], v[66:69], v[226:229], v[94:97]
	v_mfma_f32_16x16x32_bf16 v[86:89], v[78:81], v[226:229], v[86:89]
	s_barrier
	s_setprio 0
	s_add_i32 s28, 0, 0x1c000
	s_add_i32 s29, s63, s37
	v_add_u32_e32 v181, s28, v178
	v_lshl_add_u64 v[186:187], v[186:187], 0, s[94:95]
	s_mov_b32 m0, s29
	ds_read_b128 v[230:233], v181
	ds_read_b128 v[234:237], v181 offset:1024
	ds_read_b128 v[238:241], v181 offset:2048
	ds_read_b128 v[242:245], v181 offset:3072
	global_load_lds_dwordx4 v[186:187], off
	v_lshl_add_u64 v[186:187], v[246:247], 0, s[94:95]
	s_add_i32 m0, s29, 0x2000
	s_nop 0
	global_load_lds_dwordx4 v[186:187], off
	s_barrier
	s_waitcnt lgkmcnt(0)
	s_setprio 1
	v_mfma_f32_16x16x32_bf16 v[134:137], v[230:233], v[172:175], v[134:137]
	v_mfma_f32_16x16x32_bf16 v[130:133], v[238:241], v[172:175], v[130:133]
	v_mfma_f32_16x16x32_bf16 v[122:125], v[230:233], v[206:209], v[122:125]
	v_mfma_f32_16x16x32_bf16 v[114:117], v[238:241], v[206:209], v[114:117]
	v_mfma_f32_16x16x32_bf16 v[106:109], v[230:233], v[214:217], v[106:109]
	v_mfma_f32_16x16x32_bf16 v[98:101], v[238:241], v[214:217], v[98:101]
	v_mfma_f32_16x16x32_bf16 v[90:93], v[230:233], v[222:225], v[90:93]
	v_mfma_f32_16x16x32_bf16 v[82:85], v[238:241], v[222:225], v[82:85]
	v_mfma_f32_16x16x32_bf16 v[134:137], v[234:237], v[182:185], v[134:137]
	v_mfma_f32_16x16x32_bf16 v[130:133], v[242:245], v[182:185], v[130:133]
	v_mfma_f32_16x16x32_bf16 v[122:125], v[234:237], v[210:213], v[122:125]
	v_mfma_f32_16x16x32_bf16 v[114:117], v[242:245], v[210:213], v[114:117]
	v_mfma_f32_16x16x32_bf16 v[106:109], v[234:237], v[218:221], v[106:109]
	v_mfma_f32_16x16x32_bf16 v[98:101], v[242:245], v[218:221], v[98:101]
	v_mfma_f32_16x16x32_bf16 v[90:93], v[234:237], v[226:229], v[90:93]
	v_mfma_f32_16x16x32_bf16 v[82:85], v[242:245], v[226:229], v[82:85]
	s_barrier
	s_setprio 0
	s_mov_b32 m0, s59
	v_lshl_add_u64 v[186:187], v[248:249], 0, s[94:95]
	ds_read_b128 v[172:175], v180 offset:49152
	ds_read_b128 v[182:185], v180 offset:50176
	ds_read_b128 v[206:209], v180 offset:51200
	ds_read_b128 v[210:213], v180 offset:52224
	ds_read_b128 v[214:217], v180 offset:53248
	ds_read_b128 v[218:221], v180 offset:54272
	ds_read_b128 v[222:225], v180 offset:55296
	ds_read_b128 v[226:229], v180 offset:56320
	global_load_lds_dwordx4 v[186:187], off
	v_lshl_add_u64 v[186:187], v[250:251], 0, s[94:95]
	s_mov_b32 m0, s60
	s_nop 0
	global_load_lds_dwordx4 v[186:187], off
	s_barrier
	s_waitcnt lgkmcnt(0)
	s_setprio 1
	v_mfma_f32_16x16x32_bf16 v[70:73], v[62:65], v[172:175], v[70:73]
	v_mfma_f32_16x16x32_bf16 v[54:57], v[74:77], v[172:175], v[54:57]
	v_mfma_f32_16x16x32_bf16 v[46:49], v[62:65], v[206:209], v[46:49]
	v_mfma_f32_16x16x32_bf16 v[38:41], v[74:77], v[206:209], v[38:41]
	v_mfma_f32_16x16x32_bf16 v[30:33], v[62:65], v[214:217], v[30:33]
	v_mfma_f32_16x16x32_bf16 v[22:25], v[74:77], v[214:217], v[22:25]
	v_mfma_f32_16x16x32_bf16 v[14:17], v[62:65], v[222:225], v[14:17]
	v_mfma_f32_16x16x32_bf16 v[6:9], v[74:77], v[222:225], v[6:9]
	v_mfma_f32_16x16x32_bf16 v[70:73], v[66:69], v[182:185], v[70:73]
	v_mfma_f32_16x16x32_bf16 v[54:57], v[78:81], v[182:185], v[54:57]
	v_mfma_f32_16x16x32_bf16 v[46:49], v[66:69], v[210:213], v[46:49]
	v_mfma_f32_16x16x32_bf16 v[38:41], v[78:81], v[210:213], v[38:41]
	v_mfma_f32_16x16x32_bf16 v[30:33], v[66:69], v[218:221], v[30:33]
	v_mfma_f32_16x16x32_bf16 v[22:25], v[78:81], v[218:221], v[22:25]
	v_mfma_f32_16x16x32_bf16 v[14:17], v[66:69], v[226:229], v[14:17]
	v_mfma_f32_16x16x32_bf16 v[6:9], v[78:81], v[226:229], v[6:9]
	s_barrier
	s_setprio 0
	s_add_u32 s22, s22, 0x40080
	s_addc_u32 s23, s23, 0
	s_add_i32 s28, s28, s37
	v_lshl_add_u64 v[62:63], s[22:23], 0, v[0:1]
	s_mov_b32 m0, s28
	s_nop 0
	global_load_lds_dwordx4 v[62:63], off
	v_lshl_add_u64 v[62:63], s[22:23], 0, v[166:167]
	s_add_i32 m0, s28, 0x2000
	s_nop 0
	global_load_lds_dwordx4 v[62:63], off
	s_waitcnt vmcnt(6)
	s_barrier
	s_setprio 1
	v_mfma_f32_16x16x32_bf16 v[58:61], v[230:233], v[172:175], v[58:61]
	v_mfma_f32_16x16x32_bf16 v[50:53], v[238:241], v[172:175], v[50:53]
	v_mfma_f32_16x16x32_bf16 v[42:45], v[230:233], v[206:209], v[42:45]
	v_mfma_f32_16x16x32_bf16 v[34:37], v[238:241], v[206:209], v[34:37]
	v_mfma_f32_16x16x32_bf16 v[26:29], v[230:233], v[214:217], v[26:29]
	v_mfma_f32_16x16x32_bf16 v[18:21], v[238:241], v[214:217], v[18:21]
	v_mfma_f32_16x16x32_bf16 v[10:13], v[230:233], v[222:225], v[10:13]
	v_mfma_f32_16x16x32_bf16 v[2:5], v[238:241], v[222:225], v[2:5]
	v_mfma_f32_16x16x32_bf16 v[62:65], v[234:237], v[182:185], v[58:61]
	v_mfma_f32_16x16x32_bf16 v[50:53], v[242:245], v[182:185], v[50:53]
	v_mfma_f32_16x16x32_bf16 v[42:45], v[234:237], v[210:213], v[42:45]
	v_mfma_f32_16x16x32_bf16 v[34:37], v[242:245], v[210:213], v[34:37]
	v_mfma_f32_16x16x32_bf16 v[26:29], v[234:237], v[218:221], v[26:29]
	v_mfma_f32_16x16x32_bf16 v[18:21], v[242:245], v[218:221], v[18:21]
	v_mfma_f32_16x16x32_bf16 v[10:13], v[234:237], v[226:229], v[10:13]
	v_mfma_f32_16x16x32_bf16 v[2:5], v[242:245], v[226:229], v[2:5]
	s_barrier
	s_setprio 0
	s_add_i32 s49, s49, 2
	s_add_u32 s8, s8, 0x100
	s_addc_u32 s9, s9, 0
	s_add_u32 s31, s31, 0x100
	s_addc_u32 s47, s47, 0
	s_cmp_gt_u32 s49, 13
	s_cbranch_scc0 .LBB0_95
	v_lshl_or_b32 v172, s24, 7, v179
	v_ashrrev_i32_e32 v173, 31, v172
	v_lshlrev_b64 v[58:59], 2, v[172:173]
	v_lshl_add_u64 v[60:61], s[40:41], 0, v[58:59]
	v_lshl_add_u64 v[74:75], s[44:45], 0, v[58:59]
	global_load_dwordx4 v[66:69], v[60:61], off offset:16
	global_load_dwordx4 v[78:81], v[60:61], off
	s_nop 0
	global_load_dwordx4 v[58:61], v[74:75], off offset:16
	s_nop 0
	global_load_dwordx4 v[74:77], v[74:75], off
	v_lshl_add_u32 v174, s2, 8, v177
	v_ashrrev_i32_e32 v175, 31, v174
	v_lshl_add_u64 v[172:173], v[172:173], 1, s[20:21]
	v_lshlrev_b64 v[182:183], 11, v[174:175]
	s_mov_b32 s2, 0x50000
	s_mov_b32 s24, s46
	s_mov_b64 s[22:23], s[54:55]
	s_mov_b64 s[8:9], s[50:51]
	s_waitcnt vmcnt(0)
	v_add_f32_e32 v138, v138, v66
	v_add_f32_e32 v126, v126, v78
	v_add_f32_e32 v130, v130, v58
	v_mul_f32_e32 v130, 0xbfb8aa3b, v130
	v_add_f32_e32 v131, v131, v59
	v_add_f32_e32 v122, v122, v74
	v_exp_f32_e32 v130, v130
	v_mul_f32_e32 v131, 0xbfb8aa3b, v131
	v_mul_f32_e32 v122, 0xbfb8aa3b, v122
	v_add_f32_e32 v123, v123, v75
	v_exp_f32_e32 v131, v131
	v_exp_f32_e32 v122, v122
	v_mul_f32_e32 v123, 0xbfb8aa3b, v123
	v_add_f32_e32 v124, v124, v76
	v_exp_f32_e32 v123, v123
	v_mul_f32_e32 v124, 0xbfb8aa3b, v124
	v_add_f32_e32 v125, v125, v77
	v_add_f32_e32 v114, v114, v58
	v_exp_f32_e32 v124, v124
	v_mul_f32_e32 v125, 0xbfb8aa3b, v125
	v_mul_f32_e32 v114, 0xbfb8aa3b, v114
	v_add_f32_e32 v115, v115, v59
	v_add_f32_e32 v106, v106, v74
	v_add_f32_e32 v130, 1.0, v130
	v_exp_f32_e32 v125, v125
	v_exp_f32_e32 v114, v114
	v_mul_f32_e32 v115, 0xbfb8aa3b, v115
	v_mul_f32_e32 v106, 0xbfb8aa3b, v106
	v_add_f32_e32 v107, v107, v75
	v_rcp_f32_e32 v130, v130
	v_add_f32_e32 v131, 1.0, v131
	v_add_f32_e32 v122, 1.0, v122
	v_exp_f32_e32 v115, v115
	v_exp_f32_e32 v106, v106
	v_mul_f32_e32 v107, 0xbfb8aa3b, v107
	v_add_f32_e32 v108, v108, v76
	v_rcp_f32_e32 v131, v131
	v_rcp_f32_e32 v122, v122
	v_add_f32_e32 v123, 1.0, v123
	v_exp_f32_e32 v107, v107
	v_mul_f32_e32 v108, 0xbfb8aa3b, v108
	v_add_f32_e32 v109, v109, v77
	v_add_f32_e32 v98, v98, v58
	v_rcp_f32_e32 v123, v123
	v_add_f32_e32 v124, 1.0, v124
	v_exp_f32_e32 v108, v108
	v_mul_f32_e32 v109, 0xbfb8aa3b, v109
	v_mul_f32_e32 v98, 0xbfb8aa3b, v98
	v_add_f32_e32 v99, v99, v59
	v_add_f32_e32 v90, v90, v74
	v_rcp_f32_e32 v124, v124
	v_add_f32_e32 v125, 1.0, v125
	v_add_f32_e32 v114, 1.0, v114
	v_exp_f32_e32 v109, v109
	v_exp_f32_e32 v98, v98
	v_mul_f32_e32 v99, 0xbfb8aa3b, v99
	v_mul_f32_e32 v90, 0xbfb8aa3b, v90
	v_add_f32_e32 v91, v91, v75
	v_mul_f32_e32 v138, v138, v130
	v_add_f32_e32 v130, v139, v67
	v_rcp_f32_e32 v125, v125
	v_rcp_f32_e32 v114, v114
	v_add_f32_e32 v115, 1.0, v115
	v_add_f32_e32 v106, 1.0, v106
	v_exp_f32_e32 v99, v99
	v_exp_f32_e32 v90, v90
	v_mul_f32_e32 v91, 0xbfb8aa3b, v91
	v_add_f32_e32 v92, v92, v76
	v_mul_f32_e32 v139, v130, v131
	v_add_f32_e32 v131, v132, v60
	v_mul_f32_e32 v122, v126, v122
	v_add_f32_e32 v126, v127, v79
	v_rcp_f32_e32 v115, v115
	v_rcp_f32_e32 v106, v106
	v_add_f32_e32 v107, 1.0, v107
	v_exp_f32_e32 v91, v91
	v_mul_f32_e32 v92, 0xbfb8aa3b, v92
	v_add_f32_e32 v93, v93, v77
	v_add_f32_e32 v82, v82, v58
	v_mul_f32_e32 v131, 0xbfb8aa3b, v131
	v_mul_f32_e32 v123, v126, v123
	v_add_f32_e32 v126, v128, v80
	v_rcp_f32_e32 v107, v107
	v_add_f32_e32 v108, 1.0, v108
	v_exp_f32_e32 v92, v92
	v_mul_f32_e32 v93, 0xbfb8aa3b, v93
	v_mul_f32_e32 v82, 0xbfb8aa3b, v82
	v_add_f32_e32 v83, v83, v59
	v_add_f32_e32 v50, v50, v58
	v_exp_f32_e32 v131, v131
	v_mul_f32_e32 v124, v126, v124
	v_add_f32_e32 v126, v129, v81
	v_add_f32_e32 v118, v118, v66
	v_rcp_f32_e32 v108, v108
	v_add_f32_e32 v109, 1.0, v109
	v_add_f32_e32 v98, 1.0, v98
	v_exp_f32_e32 v93, v93
	v_exp_f32_e32 v82, v82
	v_mul_f32_e32 v83, 0xbfb8aa3b, v83
	v_mul_f32_e32 v50, 0xbfb8aa3b, v50
	v_add_f32_e32 v51, v51, v59
	v_mul_f32_e32 v125, v126, v125
	v_mul_f32_e32 v126, v118, v114
	v_add_f32_e32 v114, v119, v67
	v_add_f32_e32 v110, v110, v78
	v_rcp_f32_e32 v109, v109
	v_rcp_f32_e32 v98, v98
	v_add_f32_e32 v99, 1.0, v99
	v_add_f32_e32 v90, 1.0, v90
	v_exp_f32_e32 v83, v83
	v_exp_f32_e32 v50, v50
	v_mul_f32_e32 v51, 0xbfb8aa3b, v51
	v_add_f32_e32 v34, v34, v58
	v_mul_f32_e32 v127, v114, v115
	v_add_f32_e32 v115, v116, v60
	v_mul_f32_e32 v106, v110, v106
	v_add_f32_e32 v110, v111, v79
	v_rcp_f32_e32 v99, v99
	v_rcp_f32_e32 v90, v90
	v_add_f32_e32 v91, 1.0, v91
	v_exp_f32_e32 v51, v51
	v_mul_f32_e32 v34, 0xbfb8aa3b, v34
	v_add_f32_e32 v35, v35, v59
	v_mul_f32_e32 v115, 0xbfb8aa3b, v115
	v_mul_f32_e32 v107, v110, v107
	v_add_f32_e32 v110, v112, v80
	v_rcp_f32_e32 v91, v91
	v_add_f32_e32 v92, 1.0, v92
	v_exp_f32_e32 v34, v34
	v_mul_f32_e32 v35, 0xbfb8aa3b, v35
	v_add_f32_e32 v18, v18, v58
	v_add_f32_e32 v131, 1.0, v131
	v_exp_f32_e32 v115, v115
	v_mul_f32_e32 v108, v110, v108
	v_add_f32_e32 v110, v113, v81
	v_add_f32_e32 v102, v102, v66
	v_rcp_f32_e32 v92, v92
	v_add_f32_e32 v93, 1.0, v93
	v_add_f32_e32 v82, 1.0, v82
	v_exp_f32_e32 v35, v35
	v_mul_f32_e32 v18, 0xbfb8aa3b, v18
	v_add_f32_e32 v19, v19, v59
	v_rcp_f32_e32 v131, v131
	v_mul_f32_e32 v109, v110, v109
	v_mul_f32_e32 v110, v102, v98
	v_add_f32_e32 v98, v103, v67
	v_add_f32_e32 v94, v94, v78
	v_rcp_f32_e32 v93, v93
	v_rcp_f32_e32 v82, v82
	v_add_f32_e32 v83, 1.0, v83
	v_add_f32_e32 v50, 1.0, v50
	v_exp_f32_e32 v18, v18
	v_mul_f32_e32 v19, 0xbfb8aa3b, v19
	v_add_f32_e32 v2, v2, v58
	v_mul_f32_e32 v111, v98, v99
	v_add_f32_e32 v99, v100, v60
	v_mul_f32_e32 v90, v94, v90
	v_add_f32_e32 v94, v95, v79
	v_rcp_f32_e32 v83, v83
	v_rcp_f32_e32 v50, v50
	v_add_f32_e32 v51, 1.0, v51
	v_exp_f32_e32 v19, v19
	v_mul_f32_e32 v2, 0xbfb8aa3b, v2
	v_add_f32_e32 v3, v3, v59
	v_add_f32_e32 v134, v134, v74
	v_mul_f32_e32 v99, 0xbfb8aa3b, v99
	v_mul_f32_e32 v91, v94, v91
	v_add_f32_e32 v94, v96, v80
	v_rcp_f32_e32 v51, v51
	v_add_f32_e32 v34, 1.0, v34
	v_exp_f32_e32 v2, v2
	v_mul_f32_e32 v3, 0xbfb8aa3b, v3
	v_mul_f32_e32 v134, 0xbfb8aa3b, v134
	v_add_f32_e32 v135, v135, v75
	v_add_f32_e32 v130, v140, v68
	v_add_f32_e32 v115, 1.0, v115
	v_exp_f32_e32 v99, v99
	v_mul_f32_e32 v92, v94, v92
	v_add_f32_e32 v94, v97, v81
	v_add_f32_e32 v86, v86, v66
	v_rcp_f32_e32 v34, v34
	v_add_f32_e32 v35, 1.0, v35
	v_exp_f32_e32 v3, v3
	v_exp_f32_e32 v134, v134
	v_mul_f32_e32 v135, 0xbfb8aa3b, v135
	v_add_f32_e32 v136, v136, v76
	v_mul_f32_e32 v140, v130, v131
	v_add_f32_e32 v131, v133, v61
	v_rcp_f32_e32 v115, v115
	v_mul_f32_e32 v93, v94, v93
	v_mul_f32_e32 v94, v86, v82
	v_add_f32_e32 v82, v87, v67
	v_add_f32_e32 v54, v54, v66
	v_rcp_f32_e32 v35, v35
	v_add_f32_e32 v18, 1.0, v18
	v_exp_f32_e32 v135, v135
	v_mul_f32_e32 v136, 0xbfb8aa3b, v136
	v_add_f32_e32 v137, v137, v77
	v_mul_f32_e32 v131, 0xbfb8aa3b, v131
	v_mul_f32_e32 v95, v82, v83
	v_add_f32_e32 v83, v84, v60
	v_mul_f32_e32 v54, v54, v50
	v_add_f32_e32 v50, v55, v67
	v_rcp_f32_e32 v18, v18
	v_add_f32_e32 v19, 1.0, v19
	v_exp_f32_e32 v136, v136
	v_mul_f32_e32 v137, 0xbfb8aa3b, v137
	v_exp_f32_e32 v131, v131
	v_mul_f32_e32 v83, 0xbfb8aa3b, v83
	v_mul_f32_e32 v55, v50, v51
	v_add_f32_e32 v51, v52, v60
	v_add_f32_e32 v38, v38, v66
	v_rcp_f32_e32 v19, v19
	v_add_f32_e32 v2, 1.0, v2
	v_exp_f32_e32 v137, v137
	v_add_f32_e32 v114, v120, v68
	v_add_f32_e32 v99, 1.0, v99
	v_exp_f32_e32 v83, v83
	v_mul_f32_e32 v51, 0xbfb8aa3b, v51
	v_mul_f32_e32 v38, v38, v34
	v_add_f32_e32 v34, v39, v67
	v_rcp_f32_e32 v2, v2
	v_add_f32_e32 v3, 1.0, v3
	v_add_f32_e32 v134, 1.0, v134
	v_mul_f32_e32 v120, v114, v115
	v_add_f32_e32 v115, v117, v61
	v_rcp_f32_e32 v99, v99
	v_exp_f32_e32 v51, v51
	v_mul_f32_e32 v39, v34, v35
	v_add_f32_e32 v35, v36, v60
	v_add_f32_e32 v22, v22, v66
	v_rcp_f32_e32 v3, v3
	v_rcp_f32_e32 v134, v134
	v_add_f32_e32 v135, 1.0, v135
	v_mul_f32_e32 v115, 0xbfb8aa3b, v115
	v_mul_f32_e32 v35, 0xbfb8aa3b, v35
	v_mul_f32_e32 v22, v22, v18
	v_add_f32_e32 v18, v23, v67
	v_rcp_f32_e32 v135, v135
	v_add_f32_e32 v136, 1.0, v136
	v_add_f32_e32 v131, 1.0, v131
	v_exp_f32_e32 v115, v115
	v_exp_f32_e32 v35, v35
	v_mul_f32_e32 v23, v18, v19
	v_add_f32_e32 v19, v20, v60
	v_add_f32_e32 v6, v6, v66
	v_rcp_f32_e32 v136, v136
	v_add_f32_e32 v137, 1.0, v137
	v_rcp_f32_e32 v131, v131
	v_add_f32_e32 v98, v104, v68
	v_add_f32_e32 v83, 1.0, v83
	v_mul_f32_e32 v19, 0xbfb8aa3b, v19
	v_mul_f32_e32 v6, v6, v2
	v_add_f32_e32 v2, v7, v67
	v_add_f32_e32 v142, v142, v78
	v_rcp_f32_e32 v137, v137
	v_mul_f32_e32 v104, v98, v99
	v_add_f32_e32 v99, v101, v61
	v_rcp_f32_e32 v83, v83
	v_add_f32_e32 v51, 1.0, v51
	v_exp_f32_e32 v19, v19
	v_mul_f32_e32 v7, v2, v3
	v_add_f32_e32 v3, v4, v60
	v_mul_f32_e32 v134, v142, v134
	v_add_f32_e32 v142, v143, v79
	v_mul_f32_e32 v99, 0xbfb8aa3b, v99
	v_rcp_f32_e32 v51, v51
	v_mul_f32_e32 v3, 0xbfb8aa3b, v3
	v_mul_f32_e32 v135, v142, v135
	v_add_f32_e32 v142, v144, v80
	v_add_f32_e32 v130, v141, v69
	v_add_f32_e32 v115, 1.0, v115
	v_exp_f32_e32 v99, v99
	v_add_f32_e32 v62, v62, v74
	v_add_f32_e32 v35, 1.0, v35
	v_exp_f32_e32 v3, v3
	v_mul_f32_e32 v136, v142, v136
	v_add_f32_e32 v142, v145, v81
	v_mul_f32_e32 v141, v130, v131
	v_lshl_add_u64 v[130:131], v[172:173], 0, v[182:183]
	v_cvt_pk_bf16_f32 v132, v134, v135
	v_rcp_f32_e32 v115, v115
	v_add_f32_e32 v82, v88, v68
	v_mul_f32_e32 v62, 0xbfb8aa3b, v62
	v_add_f32_e32 v63, v63, v75
	v_rcp_f32_e32 v35, v35
	v_mul_f32_e32 v137, v142, v137
	v_cvt_pk_bf16_f32 v133, v136, v137
	v_cvt_pk_bf16_f32 v134, v138, v139
	v_cvt_pk_bf16_f32 v135, v140, v141
	global_store_dwordx4 v[130:131], v[132:135], off
	v_mul_f32_e32 v88, v82, v83
	v_add_f32_e32 v83, v85, v61
	v_or_b32_e32 v132, 16, v174
	v_exp_f32_e32 v62, v62
	v_mul_f32_e32 v63, 0xbfb8aa3b, v63
	v_add_f32_e32 v64, v64, v76
	v_add_f32_e32 v50, v56, v68
	v_add_f32_e32 v42, v42, v74
	v_add_f32_e32 v19, 1.0, v19
	v_ashrrev_i32_e32 v133, 31, v132
	v_mul_f32_e32 v83, 0xbfb8aa3b, v83
	v_exp_f32_e32 v63, v63
	v_mul_f32_e32 v64, 0xbfb8aa3b, v64
	v_add_f32_e32 v65, v65, v77
	v_mul_f32_e32 v56, v50, v51
	v_add_f32_e32 v51, v53, v61
	v_mul_f32_e32 v42, 0xbfb8aa3b, v42
	v_add_f32_e32 v43, v43, v75
	v_rcp_f32_e32 v19, v19
	v_lshlrev_b64 v[132:133], 11, v[132:133]
	v_add_f32_e32 v114, v121, v69
	v_add_f32_e32 v99, 1.0, v99
	v_exp_f32_e32 v83, v83
	v_exp_f32_e32 v64, v64
	v_mul_f32_e32 v65, 0xbfb8aa3b, v65
	v_mul_f32_e32 v51, 0xbfb8aa3b, v51
	v_exp_f32_e32 v42, v42
	v_mul_f32_e32 v43, 0xbfb8aa3b, v43
	v_add_f32_e32 v44, v44, v76
	v_add_f32_e32 v34, v40, v68
	v_add_f32_e32 v26, v26, v74
	v_add_f32_e32 v3, 1.0, v3
	v_mul_f32_e32 v117, v114, v115
	v_lshl_add_u64 v[118:119], v[172:173], 0, v[132:133]
	v_cvt_pk_bf16_f32 v114, v122, v123
	v_rcp_f32_e32 v99, v99
	v_exp_f32_e32 v65, v65
	v_exp_f32_e32 v51, v51
	v_exp_f32_e32 v43, v43
	v_mul_f32_e32 v44, 0xbfb8aa3b, v44
	v_add_f32_e32 v45, v45, v77
	v_mul_f32_e32 v40, v34, v35
	v_add_f32_e32 v35, v37, v61
	v_mul_f32_e32 v26, 0xbfb8aa3b, v26
	v_add_f32_e32 v27, v27, v75
	v_rcp_f32_e32 v3, v3
	v_cvt_pk_bf16_f32 v115, v124, v125
	v_cvt_pk_bf16_f32 v116, v126, v127
	v_cvt_pk_bf16_f32 v117, v120, v117
	global_store_dwordx4 v[118:119], v[114:117], off
	v_add_f32_e32 v62, 1.0, v62
	v_exp_f32_e32 v44, v44
	v_or_b32_e32 v114, 32, v174
	v_mul_f32_e32 v45, 0xbfb8aa3b, v45
	v_mul_f32_e32 v35, 0xbfb8aa3b, v35
	v_exp_f32_e32 v26, v26
	v_mul_f32_e32 v27, 0xbfb8aa3b, v27
	v_add_f32_e32 v28, v28, v76
	v_add_f32_e32 v18, v24, v68
	v_add_f32_e32 v10, v10, v74
	v_ashrrev_i32_e32 v115, 31, v114
	v_rcp_f32_e32 v62, v62
	v_add_f32_e32 v63, 1.0, v63
	v_exp_f32_e32 v45, v45
	v_exp_f32_e32 v35, v35
	v_exp_f32_e32 v27, v27
	v_mul_f32_e32 v28, 0xbfb8aa3b, v28
	v_add_f32_e32 v29, v29, v77
	v_mul_f32_e32 v24, v18, v19
	v_add_f32_e32 v19, v21, v61
	v_mul_f32_e32 v10, 0xbfb8aa3b, v10
	v_add_f32_e32 v11, v11, v75
	v_lshlrev_b64 v[114:115], 11, v[114:115]
	v_add_f32_e32 v98, v105, v69
	v_add_f32_e32 v83, 1.0, v83
	v_rcp_f32_e32 v63, v63
	v_add_f32_e32 v64, 1.0, v64
	v_add_f32_e32 v42, 1.0, v42
	v_exp_f32_e32 v28, v28
	v_mul_f32_e32 v29, 0xbfb8aa3b, v29
	v_mul_f32_e32 v19, 0xbfb8aa3b, v19
	v_exp_f32_e32 v10, v10
	v_mul_f32_e32 v11, 0xbfb8aa3b, v11
	v_add_f32_e32 v12, v12, v76
	v_add_f32_e32 v2, v8, v68
	v_mul_f32_e32 v101, v98, v99
	v_lshl_add_u64 v[102:103], v[172:173], 0, v[114:115]
	v_cvt_pk_bf16_f32 v98, v106, v107
	v_rcp_f32_e32 v83, v83
	v_rcp_f32_e32 v64, v64
	v_add_f32_e32 v65, 1.0, v65
	v_add_f32_e32 v51, 1.0, v51
	v_rcp_f32_e32 v42, v42
	v_add_f32_e32 v43, 1.0, v43
	v_exp_f32_e32 v29, v29
	v_exp_f32_e32 v19, v19
	v_exp_f32_e32 v11, v11
	v_mul_f32_e32 v12, 0xbfb8aa3b, v12
	v_add_f32_e32 v13, v13, v77
	v_mul_f32_e32 v8, v2, v3
	v_add_f32_e32 v3, v5, v61
	v_cvt_pk_bf16_f32 v99, v108, v109
	v_cvt_pk_bf16_f32 v100, v110, v111
	v_cvt_pk_bf16_f32 v101, v104, v101
	global_store_dwordx4 v[102:103], v[98:101], off
	v_add_f32_e32 v70, v70, v78
	v_rcp_f32_e32 v65, v65
	v_or_b32_e32 v98, 48, v174
	v_rcp_f32_e32 v51, v51
	v_rcp_f32_e32 v43, v43
	v_add_f32_e32 v44, 1.0, v44
	v_add_f32_e32 v26, 1.0, v26
	v_exp_f32_e32 v12, v12
	v_mul_f32_e32 v13, 0xbfb8aa3b, v13
	v_mul_f32_e32 v3, 0xbfb8aa3b, v3
	v_ashrrev_i32_e32 v99, 31, v98
	v_mul_f32_e32 v62, v70, v62
	v_add_f32_e32 v70, v71, v79
	v_rcp_f32_e32 v44, v44
	v_add_f32_e32 v45, 1.0, v45
	v_add_f32_e32 v35, 1.0, v35
	v_rcp_f32_e32 v26, v26
	v_add_f32_e32 v27, 1.0, v27
	v_exp_f32_e32 v13, v13
	v_exp_f32_e32 v3, v3
	v_lshlrev_b64 v[98:99], 11, v[98:99]
	v_add_f32_e32 v82, v89, v69
	v_mul_f32_e32 v63, v70, v63
	v_add_f32_e32 v70, v72, v80
	v_add_f32_e32 v46, v46, v78
	v_rcp_f32_e32 v45, v45
	v_rcp_f32_e32 v35, v35
	v_rcp_f32_e32 v27, v27
	v_add_f32_e32 v28, 1.0, v28
	v_add_f32_e32 v10, 1.0, v10
	v_mul_f32_e32 v85, v82, v83
	v_lshl_add_u64 v[86:87], v[172:173], 0, v[98:99]
	v_mul_f32_e32 v64, v70, v64
	v_add_f32_e32 v70, v73, v81
	v_add_f32_e32 v50, v57, v69
	v_mul_f32_e32 v42, v46, v42
	v_add_f32_e32 v46, v47, v79
	v_rcp_f32_e32 v28, v28
	v_add_f32_e32 v29, 1.0, v29
	v_add_f32_e32 v19, 1.0, v19
	v_rcp_f32_e32 v10, v10
	v_add_f32_e32 v11, 1.0, v11
	v_cvt_pk_bf16_f32 v82, v90, v91
	v_cvt_pk_bf16_f32 v83, v92, v93
	v_cvt_pk_bf16_f32 v84, v94, v95
	v_cvt_pk_bf16_f32 v85, v88, v85
	global_store_dwordx4 v[86:87], v[82:85], off
	v_mul_f32_e32 v65, v70, v65
	v_mul_f32_e32 v53, v50, v51
	v_cvt_pk_bf16_f32 v50, v62, v63
	v_cvt_pk_bf16_f32 v51, v64, v65
	v_cvt_pk_bf16_f32 v52, v54, v55
	v_add_co_u32_e32 v54, vcc, s67, v130
	v_mul_f32_e32 v43, v46, v43
	v_add_f32_e32 v46, v48, v80
	v_add_f32_e32 v30, v30, v78
	v_rcp_f32_e32 v29, v29
	v_rcp_f32_e32 v19, v19
	v_rcp_f32_e32 v11, v11
	v_add_f32_e32 v12, 1.0, v12
	v_addc_co_u32_e32 v55, vcc, 0, v131, vcc
	v_mul_f32_e32 v44, v46, v44
	v_add_f32_e32 v46, v49, v81
	v_add_f32_e32 v34, v41, v69
	v_mul_f32_e32 v26, v30, v26
	v_add_f32_e32 v30, v31, v79
	v_rcp_f32_e32 v12, v12
	v_add_f32_e32 v13, 1.0, v13
	v_add_f32_e32 v3, 1.0, v3
	v_cvt_pk_bf16_f32 v53, v56, v53
	global_store_dwordx4 v[54:55], v[50:53], off
	v_mul_f32_e32 v45, v46, v45
	v_mul_f32_e32 v37, v34, v35
	v_cvt_pk_bf16_f32 v34, v42, v43
	v_cvt_pk_bf16_f32 v35, v44, v45
	v_cvt_pk_bf16_f32 v36, v38, v39
	v_add_co_u32_e32 v38, vcc, s68, v130
	v_mul_f32_e32 v27, v30, v27
	v_add_f32_e32 v30, v32, v80
	v_add_f32_e32 v14, v14, v78
	v_rcp_f32_e32 v13, v13
	v_rcp_f32_e32 v3, v3
	v_addc_co_u32_e32 v39, vcc, 0, v131, vcc
	v_mul_f32_e32 v28, v30, v28
	v_add_f32_e32 v30, v33, v81
	v_add_f32_e32 v18, v25, v69
	v_mul_f32_e32 v10, v14, v10
	v_add_f32_e32 v14, v15, v79
	v_cvt_pk_bf16_f32 v37, v40, v37
	global_store_dwordx4 v[38:39], v[34:37], off
	v_mul_f32_e32 v29, v30, v29
	v_mul_f32_e32 v21, v18, v19
	v_cvt_pk_bf16_f32 v18, v26, v27
	v_cvt_pk_bf16_f32 v19, v28, v29
	v_cvt_pk_bf16_f32 v20, v22, v23
	v_add_co_u32_e32 v22, vcc, s2, v130
	v_mul_f32_e32 v11, v14, v11
	v_add_f32_e32 v14, v16, v80
	v_addc_co_u32_e32 v23, vcc, 0, v131, vcc
	v_mul_f32_e32 v12, v14, v12
	v_add_f32_e32 v14, v17, v81
	v_add_f32_e32 v2, v9, v69
	v_cvt_pk_bf16_f32 v21, v24, v21
	global_store_dwordx4 v[22:23], v[18:21], off
	v_mul_f32_e32 v13, v14, v13
	v_mul_f32_e32 v5, v2, v3
	v_cvt_pk_bf16_f32 v2, v10, v11
	v_cvt_pk_bf16_f32 v3, v12, v13
	v_cvt_pk_bf16_f32 v4, v6, v7
	v_add_co_u32_e32 v6, vcc, 0x58000, v130
	s_mov_b32 s2, s48
	s_nop 0
	v_addc_co_u32_e32 v7, vcc, 0, v131, vcc
	s_and_b64 vcc, exec, s[38:39]
	v_cvt_pk_bf16_f32 v5, v8, v5
	global_store_dwordx4 v[6:7], v[2:5], off
	s_cbranch_vccz .LBB0_88
	s_waitcnt vmcnt(8)
	s_cmpk_gt_u32 s35, 0xff
	s_cbranch_scc1 .LBB0_99
	s_barrier

.LBB0_260:
	s_add_u32 s22, s0, 0xfffc0080
	s_addc_u32 s23, s1, -1
	s_add_i32 s60, 0, 0x10000
	v_add_u32_e32 v142, s60, v178
	ds_read_b128 v[130:133], v142
	ds_read_b128 v[134:137], v142 offset:1024
	ds_read_b128 v[138:141], v142 offset:2048
	ds_read_b128 v[142:145], v142 offset:3072
	s_cmp_eq_u32 s59, 12
	s_cselect_b32 s47, s35, s23
	s_cselect_b32 s46, s55, s22
	s_cselect_b32 s23, s31, s58
	s_cselect_b32 s22, s56, s57
	v_lshl_add_u64 v[186:187], s[0:1], 0, v[168:169]
	s_add_i32 m0, s27, 0xc000
	ds_read_b128 v[172:175], v180
	ds_read_b128 v[182:185], v180 offset:1024
	ds_read_b128 v[206:209], v180 offset:2048
	ds_read_b128 v[210:213], v180 offset:3072
	ds_read_b128 v[214:217], v180 offset:4096
	ds_read_b128 v[218:221], v180 offset:5120
	ds_read_b128 v[222:225], v180 offset:6144
	ds_read_b128 v[226:229], v180 offset:7168
	global_load_lds_dwordx4 v[186:187], off
	v_lshl_add_u64 v[186:187], s[0:1], 0, v[170:171]
	s_add_i32 m0, s27, 0xe000
	s_nop 0
	global_load_lds_dwordx4 v[186:187], off
	s_waitcnt lgkmcnt(8)
	s_barrier
	s_waitcnt lgkmcnt(0)
	s_setprio 1
	v_mfma_f32_16x16x32_bf16 v[126:129], v[130:133], v[172:175], v[126:129]
	v_mfma_f32_16x16x32_bf16 v[122:125], v[138:141], v[172:175], v[122:125]
	v_mfma_f32_16x16x32_bf16 v[110:113], v[130:133], v[206:209], v[110:113]
	v_mfma_f32_16x16x32_bf16 v[106:109], v[138:141], v[206:209], v[106:109]
	v_mfma_f32_16x16x32_bf16 v[94:97], v[130:133], v[214:217], v[94:97]
	v_mfma_f32_16x16x32_bf16 v[90:93], v[138:141], v[214:217], v[90:93]
	v_mfma_f32_16x16x32_bf16 v[78:81], v[130:133], v[222:225], v[78:81]
	v_mfma_f32_16x16x32_bf16 v[74:77], v[138:141], v[222:225], v[74:77]
	v_mfma_f32_16x16x32_bf16 v[126:129], v[134:137], v[182:185], v[126:129]
	v_mfma_f32_16x16x32_bf16 v[122:125], v[142:145], v[182:185], v[122:125]
	v_mfma_f32_16x16x32_bf16 v[110:113], v[134:137], v[210:213], v[110:113]
	v_mfma_f32_16x16x32_bf16 v[106:109], v[142:145], v[210:213], v[106:109]
	v_mfma_f32_16x16x32_bf16 v[94:97], v[134:137], v[218:221], v[94:97]
	v_mfma_f32_16x16x32_bf16 v[90:93], v[142:145], v[218:221], v[90:93]
	v_mfma_f32_16x16x32_bf16 v[78:81], v[134:137], v[226:229], v[78:81]
	v_mfma_f32_16x16x32_bf16 v[74:77], v[142:145], v[226:229], v[74:77]
	s_barrier
	s_setprio 0
	s_add_i32 s62, 0, 0x14000
	s_add_i32 s60, s60, s25
	v_add_u32_e32 v181, s62, v178
	v_lshl_add_u64 v[186:187], s[22:23], 0, v[0:1]
	s_mov_b32 m0, s60
	ds_read_b128 v[230:233], v181
	ds_read_b128 v[234:237], v181 offset:1024
	ds_read_b128 v[238:241], v181 offset:2048
	ds_read_b128 v[242:245], v181 offset:3072
	global_load_lds_dwordx4 v[186:187], off
	v_lshl_add_u64 v[246:247], s[22:23], 0, v[162:163]
	s_add_i32 m0, s60, 0x2000
	s_nop 0
	global_load_lds_dwordx4 v[246:247], off
	s_barrier
	s_waitcnt lgkmcnt(0)
	s_setprio 1
	v_mfma_f32_16x16x32_bf16 v[118:121], v[230:233], v[172:175], v[118:121]
	v_mfma_f32_16x16x32_bf16 v[114:117], v[238:241], v[172:175], v[114:117]
	v_mfma_f32_16x16x32_bf16 v[102:105], v[230:233], v[206:209], v[102:105]
	v_mfma_f32_16x16x32_bf16 v[98:101], v[238:241], v[206:209], v[98:101]
	v_mfma_f32_16x16x32_bf16 v[86:89], v[230:233], v[214:217], v[86:89]
	v_mfma_f32_16x16x32_bf16 v[82:85], v[238:241], v[214:217], v[82:85]
	v_mfma_f32_16x16x32_bf16 v[70:73], v[230:233], v[222:225], v[70:73]
	v_mfma_f32_16x16x32_bf16 v[66:69], v[238:241], v[222:225], v[66:69]
	v_mfma_f32_16x16x32_bf16 v[118:121], v[234:237], v[182:185], v[118:121]
	v_mfma_f32_16x16x32_bf16 v[114:117], v[242:245], v[182:185], v[114:117]
	v_mfma_f32_16x16x32_bf16 v[102:105], v[234:237], v[210:213], v[102:105]
	v_mfma_f32_16x16x32_bf16 v[98:101], v[242:245], v[210:213], v[98:101]
	v_mfma_f32_16x16x32_bf16 v[86:89], v[234:237], v[218:221], v[86:89]
	v_mfma_f32_16x16x32_bf16 v[82:85], v[242:245], v[218:221], v[82:85]
	v_mfma_f32_16x16x32_bf16 v[70:73], v[234:237], v[226:229], v[70:73]
	v_mfma_f32_16x16x32_bf16 v[66:69], v[242:245], v[226:229], v[66:69]
	s_barrier
	s_setprio 0
	s_mov_b32 m0, s27
	v_lshl_add_u64 v[248:249], s[46:47], 0, v[166:167]
	ds_read_b128 v[172:175], v180 offset:16384
	ds_read_b128 v[182:185], v180 offset:17408
	ds_read_b128 v[206:209], v180 offset:18432
	ds_read_b128 v[210:213], v180 offset:19456
	ds_read_b128 v[214:217], v180 offset:20480
	ds_read_b128 v[218:221], v180 offset:21504
	ds_read_b128 v[222:225], v180 offset:22528
	ds_read_b128 v[226:229], v180 offset:23552
	global_load_lds_dwordx4 v[248:249], off
	v_lshl_add_u64 v[250:251], s[46:47], 0, v[164:165]
	s_mov_b32 m0, s45
	s_nop 0
	global_load_lds_dwordx4 v[250:251], off
	s_barrier
	s_waitcnt lgkmcnt(0)
	s_setprio 1
	v_mfma_f32_16x16x32_bf16 v[62:65], v[130:133], v[172:175], v[62:65]
	v_mfma_f32_16x16x32_bf16 v[58:61], v[138:141], v[172:175], v[58:61]
	v_mfma_f32_16x16x32_bf16 v[50:53], v[130:133], v[206:209], v[50:53]
	v_mfma_f32_16x16x32_bf16 v[42:45], v[138:141], v[206:209], v[42:45]
	v_mfma_f32_16x16x32_bf16 v[34:37], v[130:133], v[214:217], v[34:37]
	v_mfma_f32_16x16x32_bf16 v[26:29], v[138:141], v[214:217], v[26:29]
	v_mfma_f32_16x16x32_bf16 v[18:21], v[130:133], v[222:225], v[18:21]
	v_mfma_f32_16x16x32_bf16 v[10:13], v[138:141], v[222:225], v[10:13]
	v_mfma_f32_16x16x32_bf16 v[62:65], v[134:137], v[182:185], v[62:65]
	v_mfma_f32_16x16x32_bf16 v[58:61], v[142:145], v[182:185], v[58:61]
	v_mfma_f32_16x16x32_bf16 v[50:53], v[134:137], v[210:213], v[50:53]
	v_mfma_f32_16x16x32_bf16 v[42:45], v[142:145], v[210:213], v[42:45]
	v_mfma_f32_16x16x32_bf16 v[34:37], v[134:137], v[218:221], v[34:37]
	v_mfma_f32_16x16x32_bf16 v[26:29], v[142:145], v[218:221], v[26:29]
	v_mfma_f32_16x16x32_bf16 v[18:21], v[134:137], v[226:229], v[18:21]
	v_mfma_f32_16x16x32_bf16 v[10:13], v[142:145], v[226:229], v[10:13]
	s_barrier
	s_setprio 0
	s_add_u32 s60, s22, 0x40000
	s_addc_u32 s61, s23, 0
	s_add_i32 s62, s62, s25
	v_lshl_add_u64 v[130:131], s[60:61], 0, v[0:1]
	s_mov_b32 m0, s62
	s_nop 0
	global_load_lds_dwordx4 v[130:131], off
	v_lshl_add_u64 v[130:131], s[60:61], 0, v[162:163]
	s_add_i32 m0, s62, 0x2000
	s_nop 0
	global_load_lds_dwordx4 v[130:131], off
	s_waitcnt vmcnt(6)
	s_barrier
	s_setprio 1
	v_mfma_f32_16x16x32_bf16 v[54:57], v[230:233], v[172:175], v[54:57]
	v_mfma_f32_16x16x32_bf16 v[46:49], v[238:241], v[172:175], v[46:49]
	v_mfma_f32_16x16x32_bf16 v[38:41], v[230:233], v[206:209], v[38:41]
	v_mfma_f32_16x16x32_bf16 v[30:33], v[238:241], v[206:209], v[30:33]
	v_mfma_f32_16x16x32_bf16 v[22:25], v[230:233], v[214:217], v[22:25]
	v_mfma_f32_16x16x32_bf16 v[14:17], v[238:241], v[214:217], v[14:17]
	v_mfma_f32_16x16x32_bf16 v[6:9], v[230:233], v[222:225], v[6:9]
	v_mfma_f32_16x16x32_bf16 v[2:5], v[238:241], v[222:225], v[2:5]
	v_mfma_f32_16x16x32_bf16 v[54:57], v[234:237], v[182:185], v[54:57]
	v_mfma_f32_16x16x32_bf16 v[46:49], v[242:245], v[182:185], v[46:49]
	v_mfma_f32_16x16x32_bf16 v[38:41], v[234:237], v[210:213], v[38:41]
	v_mfma_f32_16x16x32_bf16 v[30:33], v[242:245], v[210:213], v[30:33]
	v_mfma_f32_16x16x32_bf16 v[22:25], v[234:237], v[218:221], v[22:25]
	v_mfma_f32_16x16x32_bf16 v[14:17], v[242:245], v[218:221], v[14:17]
	v_mfma_f32_16x16x32_bf16 v[6:9], v[234:237], v[226:229], v[6:9]
	v_mfma_f32_16x16x32_bf16 v[2:5], v[242:245], v[226:229], v[2:5]
	s_barrier
	s_setprio 0
	s_add_i32 s60, 0, 0x18000
	v_add_u32_e32 v142, s60, v178
	ds_read_b128 v[130:133], v142
	ds_read_b128 v[134:137], v142 offset:1024
	ds_read_b128 v[138:141], v142 offset:2048
	ds_read_b128 v[142:145], v142 offset:3072
	s_add_u32 s46, s46, 0x40000
	s_addc_u32 s47, s47, 0
	s_mov_b32 m0, s48
	v_lshl_add_u64 v[230:231], s[46:47], 0, v[166:167]
	ds_read_b128 v[172:175], v180 offset:32768
	ds_read_b128 v[182:185], v180 offset:33792
	ds_read_b128 v[206:209], v180 offset:34816
	ds_read_b128 v[210:213], v180 offset:35840
	ds_read_b128 v[214:217], v180 offset:36864
	ds_read_b128 v[218:221], v180 offset:37888
	ds_read_b128 v[222:225], v180 offset:38912
	ds_read_b128 v[226:229], v180 offset:39936
	global_load_lds_dwordx4 v[230:231], off
	v_lshl_add_u64 v[230:231], s[46:47], 0, v[164:165]
	s_mov_b32 m0, s49
	s_nop 0
	global_load_lds_dwordx4 v[230:231], off
	s_waitcnt lgkmcnt(8)
	s_barrier
	s_waitcnt lgkmcnt(0)
	s_setprio 1
	v_mfma_f32_16x16x32_bf16 v[126:129], v[130:133], v[172:175], v[126:129]
	v_mfma_f32_16x16x32_bf16 v[122:125], v[138:141], v[172:175], v[122:125]
	v_mfma_f32_16x16x32_bf16 v[110:113], v[130:133], v[206:209], v[110:113]
	v_mfma_f32_16x16x32_bf16 v[106:109], v[138:141], v[206:209], v[106:109]
	v_mfma_f32_16x16x32_bf16 v[94:97], v[130:133], v[214:217], v[94:97]
	v_mfma_f32_16x16x32_bf16 v[90:93], v[138:141], v[214:217], v[90:93]
	v_mfma_f32_16x16x32_bf16 v[78:81], v[130:133], v[222:225], v[78:81]
	v_mfma_f32_16x16x32_bf16 v[74:77], v[138:141], v[222:225], v[74:77]
	v_mfma_f32_16x16x32_bf16 v[126:129], v[134:137], v[182:185], v[126:129]
	v_mfma_f32_16x16x32_bf16 v[122:125], v[142:145], v[182:185], v[122:125]
	v_mfma_f32_16x16x32_bf16 v[110:113], v[134:137], v[210:213], v[110:113]
	v_mfma_f32_16x16x32_bf16 v[106:109], v[142:145], v[210:213], v[106:109]
	v_mfma_f32_16x16x32_bf16 v[94:97], v[134:137], v[218:221], v[94:97]
	v_mfma_f32_16x16x32_bf16 v[90:93], v[142:145], v[218:221], v[90:93]
	v_mfma_f32_16x16x32_bf16 v[78:81], v[134:137], v[226:229], v[78:81]
	v_mfma_f32_16x16x32_bf16 v[74:77], v[142:145], v[226:229], v[74:77]
	s_barrier
	s_setprio 0
	s_add_i32 s46, 0, 0x1c000
	s_add_i32 s47, s60, s25
	v_add_u32_e32 v181, s46, v178
	v_lshl_add_u64 v[186:187], v[186:187], 0, s[94:95]
	s_mov_b32 m0, s47
	ds_read_b128 v[230:233], v181
	ds_read_b128 v[234:237], v181 offset:1024
	ds_read_b128 v[238:241], v181 offset:2048
	ds_read_b128 v[242:245], v181 offset:3072
	global_load_lds_dwordx4 v[186:187], off
	v_lshl_add_u64 v[186:187], v[246:247], 0, s[94:95]
	s_add_i32 m0, s47, 0x2000
	s_nop 0
	global_load_lds_dwordx4 v[186:187], off
	s_barrier
	s_waitcnt lgkmcnt(0)
	s_setprio 1
	v_mfma_f32_16x16x32_bf16 v[118:121], v[230:233], v[172:175], v[118:121]
	v_mfma_f32_16x16x32_bf16 v[114:117], v[238:241], v[172:175], v[114:117]
	v_mfma_f32_16x16x32_bf16 v[102:105], v[230:233], v[206:209], v[102:105]
	v_mfma_f32_16x16x32_bf16 v[98:101], v[238:241], v[206:209], v[98:101]
	v_mfma_f32_16x16x32_bf16 v[86:89], v[230:233], v[214:217], v[86:89]
	v_mfma_f32_16x16x32_bf16 v[82:85], v[238:241], v[214:217], v[82:85]
	v_mfma_f32_16x16x32_bf16 v[70:73], v[230:233], v[222:225], v[70:73]
	v_mfma_f32_16x16x32_bf16 v[66:69], v[238:241], v[222:225], v[66:69]
	v_mfma_f32_16x16x32_bf16 v[118:121], v[234:237], v[182:185], v[118:121]
	v_mfma_f32_16x16x32_bf16 v[114:117], v[242:245], v[182:185], v[114:117]
	v_mfma_f32_16x16x32_bf16 v[102:105], v[234:237], v[210:213], v[102:105]
	v_mfma_f32_16x16x32_bf16 v[98:101], v[242:245], v[210:213], v[98:101]
	v_mfma_f32_16x16x32_bf16 v[86:89], v[234:237], v[218:221], v[86:89]
	v_mfma_f32_16x16x32_bf16 v[82:85], v[242:245], v[218:221], v[82:85]
	v_mfma_f32_16x16x32_bf16 v[70:73], v[234:237], v[226:229], v[70:73]
	v_mfma_f32_16x16x32_bf16 v[66:69], v[242:245], v[226:229], v[66:69]
	s_barrier
	s_setprio 0
	s_mov_b32 m0, s51
	v_lshl_add_u64 v[186:187], v[248:249], 0, s[94:95]
	ds_read_b128 v[172:175], v180 offset:49152
	ds_read_b128 v[182:185], v180 offset:50176
	ds_read_b128 v[206:209], v180 offset:51200
	ds_read_b128 v[210:213], v180 offset:52224
	ds_read_b128 v[214:217], v180 offset:53248
	ds_read_b128 v[218:221], v180 offset:54272
	ds_read_b128 v[222:225], v180 offset:55296
	ds_read_b128 v[226:229], v180 offset:56320
	global_load_lds_dwordx4 v[186:187], off
	v_lshl_add_u64 v[186:187], v[250:251], 0, s[94:95]
	s_mov_b32 m0, s52
	s_nop 0
	global_load_lds_dwordx4 v[186:187], off
	s_barrier
	s_waitcnt lgkmcnt(0)
	s_setprio 1
	v_mfma_f32_16x16x32_bf16 v[62:65], v[130:133], v[172:175], v[62:65]
	v_mfma_f32_16x16x32_bf16 v[58:61], v[138:141], v[172:175], v[58:61]
	v_mfma_f32_16x16x32_bf16 v[50:53], v[130:133], v[206:209], v[50:53]
	v_mfma_f32_16x16x32_bf16 v[42:45], v[138:141], v[206:209], v[42:45]
	v_mfma_f32_16x16x32_bf16 v[34:37], v[130:133], v[214:217], v[34:37]
	v_mfma_f32_16x16x32_bf16 v[26:29], v[138:141], v[214:217], v[26:29]
	v_mfma_f32_16x16x32_bf16 v[18:21], v[130:133], v[222:225], v[18:21]
	v_mfma_f32_16x16x32_bf16 v[10:13], v[138:141], v[222:225], v[10:13]
	v_mfma_f32_16x16x32_bf16 v[62:65], v[134:137], v[182:185], v[62:65]
	v_mfma_f32_16x16x32_bf16 v[58:61], v[142:145], v[182:185], v[58:61]
	v_mfma_f32_16x16x32_bf16 v[50:53], v[134:137], v[210:213], v[50:53]
	v_mfma_f32_16x16x32_bf16 v[42:45], v[142:145], v[210:213], v[42:45]
	v_mfma_f32_16x16x32_bf16 v[34:37], v[134:137], v[218:221], v[34:37]
	v_mfma_f32_16x16x32_bf16 v[26:29], v[142:145], v[218:221], v[26:29]
	v_mfma_f32_16x16x32_bf16 v[18:21], v[134:137], v[226:229], v[18:21]
	v_mfma_f32_16x16x32_bf16 v[10:13], v[142:145], v[226:229], v[10:13]
	s_barrier
	s_setprio 0
	s_add_u32 s22, s22, 0x40080
	s_addc_u32 s23, s23, 0
	s_add_i32 s46, s46, s25
	v_lshl_add_u64 v[130:131], s[22:23], 0, v[0:1]
	s_mov_b32 m0, s46
	s_nop 0
	global_load_lds_dwordx4 v[130:131], off
	v_lshl_add_u64 v[130:131], s[22:23], 0, v[162:163]
	s_add_i32 m0, s46, 0x2000
	s_nop 0
	global_load_lds_dwordx4 v[130:131], off
	s_waitcnt vmcnt(6)
	s_barrier
	s_setprio 1
	v_mfma_f32_16x16x32_bf16 v[54:57], v[230:233], v[172:175], v[54:57]
	v_mfma_f32_16x16x32_bf16 v[46:49], v[238:241], v[172:175], v[46:49]
	v_mfma_f32_16x16x32_bf16 v[38:41], v[230:233], v[206:209], v[38:41]
	v_mfma_f32_16x16x32_bf16 v[30:33], v[238:241], v[206:209], v[30:33]
	v_mfma_f32_16x16x32_bf16 v[22:25], v[230:233], v[214:217], v[22:25]
	v_mfma_f32_16x16x32_bf16 v[14:17], v[238:241], v[214:217], v[14:17]
	v_mfma_f32_16x16x32_bf16 v[6:9], v[230:233], v[222:225], v[6:9]
	v_mfma_f32_16x16x32_bf16 v[2:5], v[238:241], v[222:225], v[2:5]
	v_mfma_f32_16x16x32_bf16 v[54:57], v[234:237], v[182:185], v[54:57]
	v_mfma_f32_16x16x32_bf16 v[46:49], v[242:245], v[182:185], v[46:49]
	v_mfma_f32_16x16x32_bf16 v[38:41], v[234:237], v[210:213], v[38:41]
	v_mfma_f32_16x16x32_bf16 v[30:33], v[242:245], v[210:213], v[30:33]
	v_mfma_f32_16x16x32_bf16 v[22:25], v[234:237], v[218:221], v[22:25]
	v_mfma_f32_16x16x32_bf16 v[14:17], v[242:245], v[218:221], v[14:17]
	v_mfma_f32_16x16x32_bf16 v[6:9], v[234:237], v[226:229], v[6:9]
	v_mfma_f32_16x16x32_bf16 v[2:5], v[242:245], v[226:229], v[2:5]
	s_barrier
	s_setprio 0
	s_add_i32 s59, s59, 2
	s_add_u32 s0, s0, 0x100
	s_addc_u32 s1, s1, 0
	s_add_u32 s57, s57, 0x100
	s_addc_u32 s58, s58, 0
	s_cmp_gt_u32 s59, 13
	s_cbranch_scc0 .LBB0_260
	v_lshl_or_b32 v172, s54, 8, v179
	v_ashrrev_i32_e32 v173, 31, v172
	v_cndmask_b32_e64 v131, 0, 1, s[2:3]
	v_lshl_add_u64 v[174:175], v[172:173], 2, s[8:9]
	v_mov_b32_e32 v130, 0
	v_cmp_ne_u32_e64 s[0:1], 1, v131
	s_andn2_b64 vcc, exec, s[2:3]
	v_mov_b32_e32 v134, 0
	v_mov_b32_e32 v135, 0
	v_mov_b32_e32 v136, 0
	v_mov_b32_e32 v137, 0
	s_cbranch_vccnz .LBB0_263
	global_load_dwordx4 v[134:137], v[174:175], off

.LBB0_331:
	s_add_u32 s22, s24, 0x100
	s_addc_u32 s23, s25, 0
	s_add_i32 s52, 0, 0x10000
	v_add_u32_e32 v140, s52, v144
	ds_read_b128 v[164:167], v140
	ds_read_b128 v[168:171], v140 offset:1024
	ds_read_b128 v[172:175], v140 offset:2048
	ds_read_b128 v[176:179], v140 offset:3072
	s_cmp_eq_u32 s51, 40
	s_cselect_b32 s29, s3, s23
	s_cselect_b32 s28, s2, s22
	s_cselect_b32 s27, s1, s41
	s_cselect_b32 s26, s0, s40
	v_lshl_add_u64 v[140:141], s[24:25], 0, v[136:137]
	s_add_i32 m0, s35, 0xc000
	ds_read_b128 v[180:183], v162
	ds_read_b128 v[184:187], v162 offset:1024
	ds_read_b128 v[206:209], v162 offset:2048
	ds_read_b128 v[210:213], v162 offset:3072
	ds_read_b128 v[214:217], v162 offset:4096
	ds_read_b128 v[218:221], v162 offset:5120
	ds_read_b128 v[222:225], v162 offset:6144
	ds_read_b128 v[226:229], v162 offset:7168
	global_load_lds_dwordx4 v[140:141], off
	v_lshl_add_u64 v[140:141], s[24:25], 0, v[138:139]
	s_add_i32 m0, s35, 0xe000
	s_nop 0
	global_load_lds_dwordx4 v[140:141], off
	s_waitcnt lgkmcnt(8)
	s_barrier
	s_waitcnt lgkmcnt(0)
	s_setprio 1
	v_mfma_f32_16x16x32_bf16 v[126:129], v[164:167], v[180:183], v[126:129]
	v_mfma_f32_16x16x32_bf16 v[122:125], v[172:175], v[180:183], v[122:125]
	v_mfma_f32_16x16x32_bf16 v[114:117], v[164:167], v[206:209], v[114:117]
	v_mfma_f32_16x16x32_bf16 v[106:109], v[172:175], v[206:209], v[106:109]
	v_mfma_f32_16x16x32_bf16 v[98:101], v[164:167], v[214:217], v[98:101]
	v_mfma_f32_16x16x32_bf16 v[90:93], v[172:175], v[214:217], v[90:93]
	v_mfma_f32_16x16x32_bf16 v[82:85], v[164:167], v[222:225], v[82:85]
	v_mfma_f32_16x16x32_bf16 v[74:77], v[172:175], v[222:225], v[74:77]
	v_mfma_f32_16x16x32_bf16 v[126:129], v[168:171], v[184:187], v[126:129]
	v_mfma_f32_16x16x32_bf16 v[122:125], v[176:179], v[184:187], v[122:125]
	v_mfma_f32_16x16x32_bf16 v[114:117], v[168:171], v[210:213], v[114:117]
	v_mfma_f32_16x16x32_bf16 v[106:109], v[176:179], v[210:213], v[106:109]
	v_mfma_f32_16x16x32_bf16 v[98:101], v[168:171], v[218:221], v[98:101]
	v_mfma_f32_16x16x32_bf16 v[90:93], v[176:179], v[218:221], v[90:93]
	v_mfma_f32_16x16x32_bf16 v[82:85], v[168:171], v[226:229], v[82:85]
	v_mfma_f32_16x16x32_bf16 v[74:77], v[176:179], v[226:229], v[74:77]
	s_barrier
	s_setprio 0
	s_add_i32 s53, 0, 0x14000
	v_add_u32_e32 v140, s53, v144
	s_add_i32 s24, s52, s31
	ds_read_b128 v[230:233], v140
	ds_read_b128 v[234:237], v140 offset:1024
	ds_read_b128 v[238:241], v140 offset:2048
	ds_read_b128 v[242:245], v140 offset:3072
	v_lshl_add_u64 v[140:141], s[26:27], 0, v[0:1]
	s_mov_b32 m0, s24
	v_lshl_add_u64 v[246:247], s[26:27], 0, v[130:131]
	global_load_lds_dwordx4 v[140:141], off
	s_add_i32 m0, s24, 0x2000
	s_nop 0
	global_load_lds_dwordx4 v[246:247], off
	s_barrier
	s_waitcnt lgkmcnt(0)
	s_setprio 1
	v_mfma_f32_16x16x32_bf16 v[118:121], v[230:233], v[180:183], v[118:121]
	v_mfma_f32_16x16x32_bf16 v[110:113], v[238:241], v[180:183], v[110:113]
	v_mfma_f32_16x16x32_bf16 v[102:105], v[230:233], v[206:209], v[102:105]
	v_mfma_f32_16x16x32_bf16 v[94:97], v[238:241], v[206:209], v[94:97]
	v_mfma_f32_16x16x32_bf16 v[86:89], v[230:233], v[214:217], v[86:89]
	v_mfma_f32_16x16x32_bf16 v[78:81], v[238:241], v[214:217], v[78:81]
	v_mfma_f32_16x16x32_bf16 v[70:73], v[230:233], v[222:225], v[70:73]
	v_mfma_f32_16x16x32_bf16 v[66:69], v[238:241], v[222:225], v[66:69]
	v_mfma_f32_16x16x32_bf16 v[118:121], v[234:237], v[184:187], v[118:121]
	v_mfma_f32_16x16x32_bf16 v[110:113], v[242:245], v[184:187], v[110:113]
	v_mfma_f32_16x16x32_bf16 v[102:105], v[234:237], v[210:213], v[102:105]
	v_mfma_f32_16x16x32_bf16 v[94:97], v[242:245], v[210:213], v[94:97]
	v_mfma_f32_16x16x32_bf16 v[86:89], v[234:237], v[218:221], v[86:89]
	v_mfma_f32_16x16x32_bf16 v[78:81], v[242:245], v[218:221], v[78:81]
	v_mfma_f32_16x16x32_bf16 v[70:73], v[234:237], v[226:229], v[70:73]
	v_mfma_f32_16x16x32_bf16 v[66:69], v[242:245], v[226:229], v[66:69]
	s_barrier
	s_setprio 0
	s_mov_b32 m0, s35
	v_lshl_add_u64 v[248:249], s[28:29], 0, v[134:135]
	ds_read_b128 v[180:183], v162 offset:16384
	ds_read_b128 v[184:187], v162 offset:17408
	ds_read_b128 v[206:209], v162 offset:18432
	ds_read_b128 v[210:213], v162 offset:19456
	ds_read_b128 v[214:217], v162 offset:20480
	ds_read_b128 v[218:221], v162 offset:21504
	ds_read_b128 v[222:225], v162 offset:22528
	ds_read_b128 v[226:229], v162 offset:23552
	global_load_lds_dwordx4 v[248:249], off
	v_lshl_add_u64 v[250:251], s[28:29], 0, v[132:133]
	s_mov_b32 m0, s36
	s_nop 0
	global_load_lds_dwordx4 v[250:251], off
	s_barrier
	s_waitcnt lgkmcnt(0)
	s_setprio 1
	v_mfma_f32_16x16x32_bf16 v[62:65], v[164:167], v[180:183], v[62:65]
	v_mfma_f32_16x16x32_bf16 v[58:61], v[172:175], v[180:183], v[58:61]
	v_mfma_f32_16x16x32_bf16 v[50:53], v[164:167], v[206:209], v[50:53]
	v_mfma_f32_16x16x32_bf16 v[42:45], v[172:175], v[206:209], v[42:45]
	v_mfma_f32_16x16x32_bf16 v[34:37], v[164:167], v[214:217], v[34:37]
	v_mfma_f32_16x16x32_bf16 v[26:29], v[172:175], v[214:217], v[26:29]
	v_mfma_f32_16x16x32_bf16 v[18:21], v[164:167], v[222:225], v[18:21]
	v_mfma_f32_16x16x32_bf16 v[10:13], v[172:175], v[222:225], v[10:13]
	v_mfma_f32_16x16x32_bf16 v[62:65], v[168:171], v[184:187], v[62:65]
	v_mfma_f32_16x16x32_bf16 v[58:61], v[176:179], v[184:187], v[58:61]
	v_mfma_f32_16x16x32_bf16 v[50:53], v[168:171], v[210:213], v[50:53]
	v_mfma_f32_16x16x32_bf16 v[42:45], v[176:179], v[210:213], v[42:45]
	v_mfma_f32_16x16x32_bf16 v[34:37], v[168:171], v[218:221], v[34:37]
	v_mfma_f32_16x16x32_bf16 v[26:29], v[176:179], v[218:221], v[26:29]
	v_mfma_f32_16x16x32_bf16 v[18:21], v[168:171], v[226:229], v[18:21]
	v_mfma_f32_16x16x32_bf16 v[10:13], v[176:179], v[226:229], v[10:13]
	s_barrier
	s_setprio 0
	s_add_u32 s24, s26, 0xb0000
	s_addc_u32 s25, s27, 0
	s_add_i32 s52, s53, s31
	v_lshl_add_u64 v[164:165], s[24:25], 0, v[0:1]
	s_mov_b32 m0, s52
	s_nop 0
	global_load_lds_dwordx4 v[164:165], off
	v_lshl_add_u64 v[164:165], s[24:25], 0, v[130:131]
	s_add_i32 m0, s52, 0x2000
	s_nop 0
	global_load_lds_dwordx4 v[164:165], off
	s_waitcnt vmcnt(6)
	s_barrier
	s_setprio 1
	v_mfma_f32_16x16x32_bf16 v[54:57], v[230:233], v[180:183], v[54:57]
	v_mfma_f32_16x16x32_bf16 v[46:49], v[238:241], v[180:183], v[46:49]
	v_mfma_f32_16x16x32_bf16 v[38:41], v[230:233], v[206:209], v[38:41]
	v_mfma_f32_16x16x32_bf16 v[30:33], v[238:241], v[206:209], v[30:33]
	v_mfma_f32_16x16x32_bf16 v[22:25], v[230:233], v[214:217], v[22:25]
	v_mfma_f32_16x16x32_bf16 v[14:17], v[238:241], v[214:217], v[14:17]
	v_mfma_f32_16x16x32_bf16 v[6:9], v[230:233], v[222:225], v[6:9]
	v_mfma_f32_16x16x32_bf16 v[2:5], v[238:241], v[222:225], v[2:5]
	v_mfma_f32_16x16x32_bf16 v[54:57], v[234:237], v[184:187], v[54:57]
	v_mfma_f32_16x16x32_bf16 v[46:49], v[242:245], v[184:187], v[46:49]
	v_mfma_f32_16x16x32_bf16 v[38:41], v[234:237], v[210:213], v[38:41]
	v_mfma_f32_16x16x32_bf16 v[30:33], v[242:245], v[210:213], v[30:33]
	v_mfma_f32_16x16x32_bf16 v[22:25], v[234:237], v[218:221], v[22:25]
	v_mfma_f32_16x16x32_bf16 v[14:17], v[242:245], v[218:221], v[14:17]
	v_mfma_f32_16x16x32_bf16 v[6:9], v[234:237], v[226:229], v[6:9]
	v_mfma_f32_16x16x32_bf16 v[2:5], v[242:245], v[226:229], v[2:5]
	s_barrier
	s_setprio 0
	s_add_i32 s52, 0, 0x18000
	v_add_u32_e32 v163, s52, v144
	ds_read_b128 v[164:167], v163
	ds_read_b128 v[168:171], v163 offset:1024
	ds_read_b128 v[172:175], v163 offset:2048
	ds_read_b128 v[176:179], v163 offset:3072
	s_add_u32 s24, s28, 0xb0000
	s_addc_u32 s25, s29, 0
	s_mov_b32 m0, s37
	v_lshl_add_u64 v[230:231], s[24:25], 0, v[134:135]
	ds_read_b128 v[180:183], v162 offset:32768
	ds_read_b128 v[184:187], v162 offset:33792
	ds_read_b128 v[206:209], v162 offset:34816
	ds_read_b128 v[210:213], v162 offset:35840
	ds_read_b128 v[214:217], v162 offset:36864
	ds_read_b128 v[218:221], v162 offset:37888
	ds_read_b128 v[222:225], v162 offset:38912
	ds_read_b128 v[226:229], v162 offset:39936
	global_load_lds_dwordx4 v[230:231], off
	v_lshl_add_u64 v[230:231], s[24:25], 0, v[132:133]
	s_mov_b32 m0, s42
	s_nop 0
	global_load_lds_dwordx4 v[230:231], off
	s_waitcnt lgkmcnt(8)
	s_barrier
	s_waitcnt lgkmcnt(0)
	s_setprio 1
	v_mfma_f32_16x16x32_bf16 v[126:129], v[164:167], v[180:183], v[126:129]
	v_mfma_f32_16x16x32_bf16 v[122:125], v[172:175], v[180:183], v[122:125]
	v_mfma_f32_16x16x32_bf16 v[114:117], v[164:167], v[206:209], v[114:117]
	v_mfma_f32_16x16x32_bf16 v[106:109], v[172:175], v[206:209], v[106:109]
	v_mfma_f32_16x16x32_bf16 v[98:101], v[164:167], v[214:217], v[98:101]
	v_mfma_f32_16x16x32_bf16 v[90:93], v[172:175], v[214:217], v[90:93]
	v_mfma_f32_16x16x32_bf16 v[82:85], v[164:167], v[222:225], v[82:85]
	v_mfma_f32_16x16x32_bf16 v[74:77], v[172:175], v[222:225], v[74:77]
	v_mfma_f32_16x16x32_bf16 v[126:129], v[168:171], v[184:187], v[126:129]
	v_mfma_f32_16x16x32_bf16 v[122:125], v[176:179], v[184:187], v[122:125]
	v_mfma_f32_16x16x32_bf16 v[114:117], v[168:171], v[210:213], v[114:117]
	v_mfma_f32_16x16x32_bf16 v[106:109], v[176:179], v[210:213], v[106:109]
	v_mfma_f32_16x16x32_bf16 v[98:101], v[168:171], v[218:221], v[98:101]
	v_mfma_f32_16x16x32_bf16 v[90:93], v[176:179], v[218:221], v[90:93]
	v_mfma_f32_16x16x32_bf16 v[82:85], v[168:171], v[226:229], v[82:85]
	v_mfma_f32_16x16x32_bf16 v[74:77], v[176:179], v[226:229], v[74:77]
	s_barrier
	s_setprio 0
	s_add_i32 s28, 0, 0x1c000
	s_add_i32 s24, s52, s31
	v_add_u32_e32 v163, s28, v144
	v_lshl_add_u64 v[140:141], v[140:141], 0, s[94:95]
	s_mov_b32 m0, s24
	ds_read_b128 v[230:233], v163
	ds_read_b128 v[234:237], v163 offset:1024
	ds_read_b128 v[238:241], v163 offset:2048
	ds_read_b128 v[242:245], v163 offset:3072
	global_load_lds_dwordx4 v[140:141], off
	v_lshl_add_u64 v[140:141], v[246:247], 0, s[94:95]
	s_add_i32 m0, s24, 0x2000
	s_nop 0
	global_load_lds_dwordx4 v[140:141], off
	s_barrier
	s_waitcnt lgkmcnt(0)
	s_setprio 1
	v_mfma_f32_16x16x32_bf16 v[118:121], v[230:233], v[180:183], v[118:121]
	v_mfma_f32_16x16x32_bf16 v[110:113], v[238:241], v[180:183], v[110:113]
	v_mfma_f32_16x16x32_bf16 v[102:105], v[230:233], v[206:209], v[102:105]
	v_mfma_f32_16x16x32_bf16 v[94:97], v[238:241], v[206:209], v[94:97]
	v_mfma_f32_16x16x32_bf16 v[86:89], v[230:233], v[214:217], v[86:89]
	v_mfma_f32_16x16x32_bf16 v[78:81], v[238:241], v[214:217], v[78:81]
	v_mfma_f32_16x16x32_bf16 v[70:73], v[230:233], v[222:225], v[70:73]
	v_mfma_f32_16x16x32_bf16 v[66:69], v[238:241], v[222:225], v[66:69]
	v_mfma_f32_16x16x32_bf16 v[118:121], v[234:237], v[184:187], v[118:121]
	v_mfma_f32_16x16x32_bf16 v[110:113], v[242:245], v[184:187], v[110:113]
	v_mfma_f32_16x16x32_bf16 v[102:105], v[234:237], v[210:213], v[102:105]
	v_mfma_f32_16x16x32_bf16 v[94:97], v[242:245], v[210:213], v[94:97]
	v_mfma_f32_16x16x32_bf16 v[86:89], v[234:237], v[218:221], v[86:89]
	v_mfma_f32_16x16x32_bf16 v[78:81], v[242:245], v[218:221], v[78:81]
	v_mfma_f32_16x16x32_bf16 v[70:73], v[234:237], v[226:229], v[70:73]
	v_mfma_f32_16x16x32_bf16 v[66:69], v[242:245], v[226:229], v[66:69]
	s_barrier
	s_setprio 0
	s_mov_b32 m0, s44
	v_lshl_add_u64 v[140:141], v[248:249], 0, s[94:95]
	ds_read_b128 v[180:183], v162 offset:49152
	ds_read_b128 v[184:187], v162 offset:50176
	ds_read_b128 v[206:209], v162 offset:51200
	ds_read_b128 v[210:213], v162 offset:52224
	ds_read_b128 v[214:217], v162 offset:53248
	ds_read_b128 v[218:221], v162 offset:54272
	ds_read_b128 v[222:225], v162 offset:55296
	ds_read_b128 v[226:229], v162 offset:56320
	global_load_lds_dwordx4 v[140:141], off
	v_lshl_add_u64 v[140:141], v[250:251], 0, s[94:95]
	s_mov_b32 m0, s45
	s_nop 0
	global_load_lds_dwordx4 v[140:141], off
	s_barrier
	s_waitcnt lgkmcnt(0)
	s_setprio 1
	v_mfma_f32_16x16x32_bf16 v[62:65], v[164:167], v[180:183], v[62:65]
	v_mfma_f32_16x16x32_bf16 v[58:61], v[172:175], v[180:183], v[58:61]
	v_mfma_f32_16x16x32_bf16 v[50:53], v[164:167], v[206:209], v[50:53]
	v_mfma_f32_16x16x32_bf16 v[42:45], v[172:175], v[206:209], v[42:45]
	v_mfma_f32_16x16x32_bf16 v[34:37], v[164:167], v[214:217], v[34:37]
	v_mfma_f32_16x16x32_bf16 v[26:29], v[172:175], v[214:217], v[26:29]
	v_mfma_f32_16x16x32_bf16 v[18:21], v[164:167], v[222:225], v[18:21]
	v_mfma_f32_16x16x32_bf16 v[10:13], v[172:175], v[222:225], v[10:13]
	v_mfma_f32_16x16x32_bf16 v[62:65], v[168:171], v[184:187], v[62:65]
	v_mfma_f32_16x16x32_bf16 v[58:61], v[176:179], v[184:187], v[58:61]
	v_mfma_f32_16x16x32_bf16 v[50:53], v[168:171], v[210:213], v[50:53]
	v_mfma_f32_16x16x32_bf16 v[42:45], v[176:179], v[210:213], v[42:45]
	v_mfma_f32_16x16x32_bf16 v[34:37], v[168:171], v[218:221], v[34:37]
	v_mfma_f32_16x16x32_bf16 v[26:29], v[176:179], v[218:221], v[26:29]
	v_mfma_f32_16x16x32_bf16 v[18:21], v[168:171], v[226:229], v[18:21]
	v_mfma_f32_16x16x32_bf16 v[10:13], v[176:179], v[226:229], v[10:13]
	s_barrier
	s_setprio 0
	s_add_u32 s24, s26, 0xb0080
	s_addc_u32 s25, s27, 0
	s_add_i32 s26, s28, s31
	v_lshl_add_u64 v[140:141], s[24:25], 0, v[0:1]
	s_mov_b32 m0, s26
	s_nop 0
	global_load_lds_dwordx4 v[140:141], off
	v_lshl_add_u64 v[140:141], s[24:25], 0, v[130:131]
	s_add_i32 m0, s26, 0x2000
	s_nop 0
	global_load_lds_dwordx4 v[140:141], off
	s_waitcnt vmcnt(6)
	s_barrier
	s_setprio 1
	v_mfma_f32_16x16x32_bf16 v[54:57], v[230:233], v[180:183], v[54:57]
	v_mfma_f32_16x16x32_bf16 v[46:49], v[238:241], v[180:183], v[46:49]
	v_mfma_f32_16x16x32_bf16 v[38:41], v[230:233], v[206:209], v[38:41]
	v_mfma_f32_16x16x32_bf16 v[30:33], v[238:241], v[206:209], v[30:33]
	v_mfma_f32_16x16x32_bf16 v[22:25], v[230:233], v[214:217], v[22:25]
	v_mfma_f32_16x16x32_bf16 v[14:17], v[238:241], v[214:217], v[14:17]
	v_mfma_f32_16x16x32_bf16 v[6:9], v[230:233], v[222:225], v[6:9]
	v_mfma_f32_16x16x32_bf16 v[2:5], v[238:241], v[222:225], v[2:5]
	v_mfma_f32_16x16x32_bf16 v[54:57], v[234:237], v[184:187], v[54:57]
	v_mfma_f32_16x16x32_bf16 v[46:49], v[242:245], v[184:187], v[46:49]
	v_mfma_f32_16x16x32_bf16 v[38:41], v[234:237], v[210:213], v[38:41]
	v_mfma_f32_16x16x32_bf16 v[30:33], v[242:245], v[210:213], v[30:33]
	v_mfma_f32_16x16x32_bf16 v[22:25], v[234:237], v[218:221], v[22:25]
	v_mfma_f32_16x16x32_bf16 v[14:17], v[242:245], v[218:221], v[14:17]
	v_mfma_f32_16x16x32_bf16 v[6:9], v[234:237], v[226:229], v[6:9]
	v_mfma_f32_16x16x32_bf16 v[2:5], v[242:245], v[226:229], v[2:5]
	s_barrier
	s_setprio 0
	s_add_i32 s51, s51, 2
	s_add_u32 s40, s40, 0x100
	s_addc_u32 s41, s41, 0
	s_cmp_gt_u32 s51, 41
	s_mov_b64 s[24:25], s[22:23]
	s_cbranch_scc0 .LBB0_331
	v_lshl_or_b32 v140, s50, 8, v145
	v_lshl_add_u32 v164, s49, 8, v143
	v_ashrrev_i32_e32 v141, 31, v140
	v_ashrrev_i32_e32 v165, 31, v164
	v_lshl_add_u64 v[166:167], v[140:141], 1, s[20:21]
	v_lshlrev_b64 v[140:141], 11, v[164:165]
	v_lshl_add_u64 v[140:141], v[166:167], 0, v[140:141]
	v_pk_add_f32 v[128:129], v[128:129], 0 op_sel_hi:[1,0]
	v_pk_add_f32 v[126:127], v[126:127], 0 op_sel_hi:[1,0]
	v_pk_add_f32 v[168:169], v[124:125], 0 op_sel_hi:[1,0]
	v_pk_add_f32 v[124:125], v[122:123], 0 op_sel_hi:[1,0]
	v_cvt_pk_bf16_f32 v122, v126, v127
	v_cvt_pk_bf16_f32 v123, v128, v129
	v_pk_add_f32 v[118:119], v[118:119], 0 op_sel_hi:[1,0]
	v_cvt_pk_bf16_f32 v124, v124, v125
	v_cvt_pk_bf16_f32 v125, v168, v169
	global_store_dwordx4 v[140:141], v[122:125], off
	v_pk_add_f32 v[120:121], v[120:121], 0 op_sel_hi:[1,0]
	v_pk_add_f32 v[114:115], v[114:115], 0 op_sel_hi:[1,0]
	v_pk_add_f32 v[122:123], v[112:113], 0 op_sel_hi:[1,0]
	v_pk_add_f32 v[112:113], v[110:111], 0 op_sel_hi:[1,0]
	v_cvt_pk_bf16_f32 v110, v118, v119
	v_cvt_pk_bf16_f32 v111, v120, v121
	v_pk_add_f32 v[102:103], v[102:103], 0 op_sel_hi:[1,0]
	v_cvt_pk_bf16_f32 v112, v112, v113
	v_cvt_pk_bf16_f32 v113, v122, v123
	global_store_dwordx4 v[140:141], v[110:113], off offset:256
	v_pk_add_f32 v[104:105], v[104:105], 0 op_sel_hi:[1,0]
	v_pk_add_f32 v[98:99], v[98:99], 0 op_sel_hi:[1,0]
	v_or_b32_e32 v110, 16, v164
	v_ashrrev_i32_e32 v111, 31, v110
	v_lshlrev_b64 v[110:111], 11, v[110:111]
	v_lshl_add_u64 v[110:111], v[166:167], 0, v[110:111]
	v_pk_add_f32 v[112:113], v[116:117], 0 op_sel_hi:[1,0]
	v_pk_add_f32 v[116:117], v[108:109], 0 op_sel_hi:[1,0]
	v_pk_add_f32 v[108:109], v[106:107], 0 op_sel_hi:[1,0]
	v_cvt_pk_bf16_f32 v106, v114, v115
	v_cvt_pk_bf16_f32 v107, v112, v113
	v_pk_add_f32 v[86:87], v[86:87], 0 op_sel_hi:[1,0]
	v_cvt_pk_bf16_f32 v108, v108, v109
	v_cvt_pk_bf16_f32 v109, v116, v117
	global_store_dwordx4 v[110:111], v[106:109], off
	v_pk_add_f32 v[88:89], v[88:89], 0 op_sel_hi:[1,0]
	v_pk_add_f32 v[82:83], v[82:83], 0 op_sel_hi:[1,0]
	v_pk_add_f32 v[106:107], v[96:97], 0 op_sel_hi:[1,0]
	v_pk_add_f32 v[96:97], v[94:95], 0 op_sel_hi:[1,0]
	v_cvt_pk_bf16_f32 v94, v102, v103
	v_cvt_pk_bf16_f32 v95, v104, v105
	v_pk_add_f32 v[72:73], v[72:73], 0 op_sel_hi:[1,0]
	v_cvt_pk_bf16_f32 v96, v96, v97
	v_cvt_pk_bf16_f32 v97, v106, v107
	global_store_dwordx4 v[110:111], v[94:97], off offset:256
	v_pk_add_f32 v[70:71], v[70:71], 0 op_sel_hi:[1,0]
	v_pk_add_f32 v[62:63], v[62:63], 0 op_sel_hi:[1,0]
	v_or_b32_e32 v94, 32, v164
	v_ashrrev_i32_e32 v95, 31, v94
	v_lshlrev_b64 v[94:95], 11, v[94:95]
	v_lshl_add_u64 v[94:95], v[166:167], 0, v[94:95]
	v_pk_add_f32 v[96:97], v[100:101], 0 op_sel_hi:[1,0]
	v_pk_add_f32 v[100:101], v[92:93], 0 op_sel_hi:[1,0]
	v_pk_add_f32 v[92:93], v[90:91], 0 op_sel_hi:[1,0]
	v_cvt_pk_bf16_f32 v90, v98, v99
	v_cvt_pk_bf16_f32 v91, v96, v97
	v_pk_add_f32 v[64:65], v[64:65], 0 op_sel_hi:[1,0]
	v_cvt_pk_bf16_f32 v92, v92, v93
	v_cvt_pk_bf16_f32 v93, v100, v101
	global_store_dwordx4 v[94:95], v[90:93], off
	s_mov_b64 s[22:23], 0x40000
	v_pk_add_f32 v[56:57], v[56:57], 0 op_sel_hi:[1,0]
	v_pk_add_f32 v[90:91], v[80:81], 0 op_sel_hi:[1,0]
	v_pk_add_f32 v[80:81], v[78:79], 0 op_sel_hi:[1,0]
	v_cvt_pk_bf16_f32 v78, v86, v87
	v_cvt_pk_bf16_f32 v79, v88, v89
	v_pk_add_f32 v[54:55], v[54:55], 0 op_sel_hi:[1,0]
	v_cvt_pk_bf16_f32 v80, v80, v81
	v_cvt_pk_bf16_f32 v81, v90, v91
	global_store_dwordx4 v[94:95], v[78:81], off offset:256
	v_pk_add_f32 v[50:51], v[50:51], 0 op_sel_hi:[1,0]
	v_pk_add_f32 v[40:41], v[40:41], 0 op_sel_hi:[1,0]
	v_or_b32_e32 v78, 48, v164
	v_ashrrev_i32_e32 v79, 31, v78
	v_lshlrev_b64 v[78:79], 11, v[78:79]
	v_lshl_add_u64 v[78:79], v[166:167], 0, v[78:79]
	v_pk_add_f32 v[80:81], v[84:85], 0 op_sel_hi:[1,0]
	v_pk_add_f32 v[84:85], v[76:77], 0 op_sel_hi:[1,0]
	v_pk_add_f32 v[76:77], v[74:75], 0 op_sel_hi:[1,0]
	v_cvt_pk_bf16_f32 v74, v82, v83
	v_cvt_pk_bf16_f32 v75, v80, v81
	v_pk_add_f32 v[38:39], v[38:39], 0 op_sel_hi:[1,0]
	v_cvt_pk_bf16_f32 v76, v76, v77
	v_cvt_pk_bf16_f32 v77, v84, v85
	global_store_dwordx4 v[78:79], v[74:77], off
	v_pk_add_f32 v[34:35], v[34:35], 0 op_sel_hi:[1,0]
	v_pk_add_f32 v[24:25], v[24:25], 0 op_sel_hi:[1,0]
	v_pk_add_f32 v[74:75], v[68:69], 0 op_sel_hi:[1,0]
	v_pk_add_f32 v[68:69], v[66:67], 0 op_sel_hi:[1,0]
	v_cvt_pk_bf16_f32 v66, v70, v71
	v_cvt_pk_bf16_f32 v67, v72, v73
	v_pk_add_f32 v[22:23], v[22:23], 0 op_sel_hi:[1,0]
	v_cvt_pk_bf16_f32 v68, v68, v69
	v_cvt_pk_bf16_f32 v69, v74, v75
	global_store_dwordx4 v[78:79], v[66:69], off offset:256
	v_pk_add_f32 v[18:19], v[18:19], 0 op_sel_hi:[1,0]
	s_mov_b32 s50, s47
	v_pk_add_f32 v[68:69], v[60:61], 0 op_sel_hi:[1,0]
	v_pk_add_f32 v[60:61], v[58:59], 0 op_sel_hi:[1,0]
	v_cvt_pk_bf16_f32 v58, v62, v63
	v_add_co_u32_e32 v62, vcc, s67, v140
	v_cvt_pk_bf16_f32 v59, v64, v65
	v_cvt_pk_bf16_f32 v60, v60, v61
	v_cvt_pk_bf16_f32 v61, v68, v69
	v_lshl_add_u64 v[66:67], v[140:141], 0, s[22:23]
	s_nop 0
	v_addc_co_u32_e32 v63, vcc, 0, v141, vcc
	global_store_dwordx4 v[62:63], v[58:61], off
	s_mov_b64 s[22:23], 0x48000
	s_mov_b32 s49, s48
	v_pk_add_f32 v[58:59], v[48:49], 0 op_sel_hi:[1,0]
	v_pk_add_f32 v[48:49], v[46:47], 0 op_sel_hi:[1,0]
	v_cvt_pk_bf16_f32 v46, v54, v55
	v_cvt_pk_bf16_f32 v47, v56, v57
	s_mov_b64 s[24:25], s[2:3]
	v_cvt_pk_bf16_f32 v48, v48, v49
	v_cvt_pk_bf16_f32 v49, v58, v59
	global_store_dwordx4 v[66:67], v[46:49], off offset:256
	v_pk_add_f32 v[8:9], v[8:9], 0 op_sel_hi:[1,0]
	v_pk_add_f32 v[6:7], v[6:7], 0 op_sel_hi:[1,0]
	v_pk_add_f32 v[48:49], v[52:53], 0 op_sel_hi:[1,0]
	v_pk_add_f32 v[52:53], v[44:45], 0 op_sel_hi:[1,0]
	v_pk_add_f32 v[44:45], v[42:43], 0 op_sel_hi:[1,0]
	v_cvt_pk_bf16_f32 v42, v50, v51
	v_cvt_pk_bf16_f32 v43, v48, v49
	v_add_co_u32_e32 v48, vcc, s68, v140
	v_cvt_pk_bf16_f32 v44, v44, v45
	v_cvt_pk_bf16_f32 v45, v52, v53
	v_lshl_add_u64 v[46:47], v[140:141], 0, s[22:23]
	s_nop 0
	v_addc_co_u32_e32 v49, vcc, 0, v141, vcc
	global_store_dwordx4 v[48:49], v[42:45], off
	s_mov_b64 s[22:23], 0x50000
	s_nop 0
	v_pk_add_f32 v[42:43], v[32:33], 0 op_sel_hi:[1,0]
	v_pk_add_f32 v[32:33], v[30:31], 0 op_sel_hi:[1,0]
	v_cvt_pk_bf16_f32 v30, v38, v39
	v_cvt_pk_bf16_f32 v31, v40, v41
	s_nop 0
	v_cvt_pk_bf16_f32 v32, v32, v33
	v_cvt_pk_bf16_f32 v33, v42, v43
	global_store_dwordx4 v[46:47], v[30:33], off offset:256
	s_nop 1
	v_lshl_add_u64 v[30:31], v[140:141], 0, s[22:23]
	v_pk_add_f32 v[32:33], v[36:37], 0 op_sel_hi:[1,0]
	s_mov_b32 s22, 0x50000
	v_pk_add_f32 v[36:37], v[28:29], 0 op_sel_hi:[1,0]
	v_pk_add_f32 v[28:29], v[26:27], 0 op_sel_hi:[1,0]
	v_cvt_pk_bf16_f32 v26, v34, v35
	v_cvt_pk_bf16_f32 v27, v32, v33
	v_add_co_u32_e32 v32, vcc, s22, v140
	v_cvt_pk_bf16_f32 v28, v28, v29
	v_cvt_pk_bf16_f32 v29, v36, v37
	s_mov_b64 s[22:23], 0x58000
	s_nop 0
	v_addc_co_u32_e32 v33, vcc, 0, v141, vcc
	global_store_dwordx4 v[32:33], v[26:29], off
	s_nop 1
	v_pk_add_f32 v[26:27], v[16:17], 0 op_sel_hi:[1,0]
	v_pk_add_f32 v[16:17], v[14:15], 0 op_sel_hi:[1,0]
	v_cvt_pk_bf16_f32 v14, v22, v23
	v_cvt_pk_bf16_f32 v15, v24, v25
	s_nop 0
	v_cvt_pk_bf16_f32 v16, v16, v17
	v_cvt_pk_bf16_f32 v17, v26, v27
	global_store_dwordx4 v[30:31], v[14:17], off offset:256
	s_nop 1
	v_lshl_add_u64 v[14:15], v[140:141], 0, s[22:23]
	v_pk_add_f32 v[16:17], v[20:21], 0 op_sel_hi:[1,0]
	s_mov_b32 s22, 0x58000
	v_pk_add_f32 v[20:21], v[12:13], 0 op_sel_hi:[1,0]
	v_pk_add_f32 v[12:13], v[10:11], 0 op_sel_hi:[1,0]
	v_cvt_pk_bf16_f32 v10, v18, v19
	v_cvt_pk_bf16_f32 v11, v16, v17
	v_add_co_u32_e32 v16, vcc, s22, v140
	v_cvt_pk_bf16_f32 v12, v12, v13
	v_cvt_pk_bf16_f32 v13, v20, v21
	s_mov_b64 s[22:23], s[0:1]
	s_nop 0
	v_addc_co_u32_e32 v17, vcc, 0, v141, vcc
	global_store_dwordx4 v[16:17], v[10:13], off
	s_and_b64 vcc, exec, s[38:39]
	s_nop 0
	v_pk_add_f32 v[10:11], v[4:5], 0 op_sel_hi:[1,0]
	v_pk_add_f32 v[4:5], v[2:3], 0 op_sel_hi:[1,0]
	v_cvt_pk_bf16_f32 v2, v6, v7
	v_cvt_pk_bf16_f32 v3, v8, v9
	s_nop 0
	v_cvt_pk_bf16_f32 v4, v4, v5
	v_cvt_pk_bf16_f32 v5, v10, v11
	global_store_dwordx4 v[14:15], v[2:5], off offset:256
	s_cbranch_vccz .LBB0_320
	s_waitcnt vmcnt(16)
	s_cmpk_gt_u32 s30, 0xff
	s_cbranch_scc1 .LBB0_335
	s_barrier

.LBB0_360:
	s_add_u32 s44, s42, 0xfffc0080
	s_addc_u32 s45, s43, -1
	s_add_i32 s63, 0, 0x10000
	v_add_u32_e32 v0, s63, v206
	ds_read_b128 v[82:85], v0
	ds_read_b128 v[86:89], v0 offset:1024
	ds_read_b128 v[90:93], v0 offset:2048
	ds_read_b128 v[94:97], v0 offset:3072
	s_cmp_eq_u32 s62, 12
	s_cselect_b32 s47, s1, s45
	s_cselect_b32 s46, s3, s44
	s_cselect_b32 s45, s31, s61
	s_cselect_b32 s44, s35, s60
	v_lshl_add_u64 v[230:231], s[42:43], 0, v[174:175]
	s_add_i32 m0, s51, 0xc000
	ds_read_b128 v[176:179], v208
	ds_read_b128 v[180:183], v208 offset:1024
	ds_read_b128 v[184:187], v208 offset:2048
	ds_read_b128 v[210:213], v208 offset:3072
	ds_read_b128 v[214:217], v208 offset:4096
	ds_read_b128 v[218:221], v208 offset:5120
	ds_read_b128 v[222:225], v208 offset:6144
	ds_read_b128 v[226:229], v208 offset:7168
	global_load_lds_dwordx4 v[230:231], off
	v_lshl_add_u64 v[230:231], s[42:43], 0, v[172:173]
	s_add_i32 m0, s51, 0xe000
	s_nop 0
	global_load_lds_dwordx4 v[230:231], off
	s_waitcnt lgkmcnt(8)
	s_barrier
	s_waitcnt lgkmcnt(0)
	s_setprio 1
	v_mfma_f32_16x16x32_bf16 v[142:145], v[82:85], v[176:179], v[142:145]
	v_mfma_f32_16x16x32_bf16 v[138:141], v[90:93], v[176:179], v[138:141]
	v_mfma_f32_16x16x32_bf16 v[126:129], v[82:85], v[184:187], v[126:129]
	v_mfma_f32_16x16x32_bf16 v[122:125], v[90:93], v[184:187], v[122:125]
	v_mfma_f32_16x16x32_bf16 v[110:113], v[82:85], v[214:217], v[110:113]
	v_mfma_f32_16x16x32_bf16 v[106:109], v[90:93], v[214:217], v[106:109]
	v_mfma_f32_16x16x32_bf16 v[78:81], v[82:85], v[222:225], v[78:81]
	v_mfma_f32_16x16x32_bf16 v[74:77], v[90:93], v[222:225], v[74:77]
	v_mfma_f32_16x16x32_bf16 v[142:145], v[86:89], v[180:183], v[142:145]
	v_mfma_f32_16x16x32_bf16 v[138:141], v[94:97], v[180:183], v[138:141]
	v_mfma_f32_16x16x32_bf16 v[126:129], v[86:89], v[210:213], v[126:129]
	v_mfma_f32_16x16x32_bf16 v[122:125], v[94:97], v[210:213], v[122:125]
	v_mfma_f32_16x16x32_bf16 v[110:113], v[86:89], v[218:221], v[110:113]
	v_mfma_f32_16x16x32_bf16 v[106:109], v[94:97], v[218:221], v[106:109]
	v_mfma_f32_16x16x32_bf16 v[78:81], v[86:89], v[226:229], v[78:81]
	v_mfma_f32_16x16x32_bf16 v[74:77], v[94:97], v[226:229], v[74:77]
	s_barrier
	s_setprio 0
	s_add_i32 s66, 0, 0x14000
	s_add_i32 s63, s63, s50
	v_add_u32_e32 v0, s66, v206
	v_lshl_add_u64 v[246:247], s[44:45], 0, v[164:165]
	s_mov_b32 m0, s63
	ds_read_b128 v[230:233], v0
	ds_read_b128 v[234:237], v0 offset:1024
	ds_read_b128 v[238:241], v0 offset:2048
	ds_read_b128 v[242:245], v0 offset:3072
	global_load_lds_dwordx4 v[246:247], off
	v_lshl_add_u64 v[248:249], s[44:45], 0, v[168:169]
	s_add_i32 m0, s63, 0x2000
	s_nop 0
	global_load_lds_dwordx4 v[248:249], off
	s_barrier
	s_waitcnt lgkmcnt(0)
	s_setprio 1
	v_mfma_f32_16x16x32_bf16 v[134:137], v[230:233], v[176:179], v[134:137]
	v_mfma_f32_16x16x32_bf16 v[130:133], v[238:241], v[176:179], v[130:133]
	v_mfma_f32_16x16x32_bf16 v[118:121], v[230:233], v[184:187], v[118:121]
	v_mfma_f32_16x16x32_bf16 v[114:117], v[238:241], v[184:187], v[114:117]
	v_mfma_f32_16x16x32_bf16 v[102:105], v[230:233], v[214:217], v[102:105]
	v_mfma_f32_16x16x32_bf16 v[98:101], v[238:241], v[214:217], v[98:101]
	v_mfma_f32_16x16x32_bf16 v[70:73], v[230:233], v[222:225], v[70:73]
	v_mfma_f32_16x16x32_bf16 v[66:69], v[238:241], v[222:225], v[66:69]
	v_mfma_f32_16x16x32_bf16 v[134:137], v[234:237], v[180:183], v[134:137]
	v_mfma_f32_16x16x32_bf16 v[130:133], v[242:245], v[180:183], v[130:133]
	v_mfma_f32_16x16x32_bf16 v[118:121], v[234:237], v[210:213], v[118:121]
	v_mfma_f32_16x16x32_bf16 v[114:117], v[242:245], v[210:213], v[114:117]
	v_mfma_f32_16x16x32_bf16 v[102:105], v[234:237], v[218:221], v[102:105]
	v_mfma_f32_16x16x32_bf16 v[98:101], v[242:245], v[218:221], v[98:101]
	v_mfma_f32_16x16x32_bf16 v[70:73], v[234:237], v[226:229], v[70:73]
	v_mfma_f32_16x16x32_bf16 v[66:69], v[242:245], v[226:229], v[66:69]
	s_barrier
	s_setprio 0
	s_mov_b32 m0, s51
	v_lshl_add_u64 v[250:251], s[46:47], 0, v[162:163]
	ds_read_b128 v[176:179], v208 offset:16384
	ds_read_b128 v[180:183], v208 offset:17408
	ds_read_b128 v[184:187], v208 offset:18432
	ds_read_b128 v[210:213], v208 offset:19456
	ds_read_b128 v[214:217], v208 offset:20480
	ds_read_b128 v[218:221], v208 offset:21504
	ds_read_b128 v[222:225], v208 offset:22528
	ds_read_b128 v[226:229], v208 offset:23552
	global_load_lds_dwordx4 v[250:251], off
	v_lshl_add_u64 v[252:253], s[46:47], 0, v[166:167]
	s_mov_b32 m0, s52
	s_nop 0
	global_load_lds_dwordx4 v[252:253], off
	s_barrier
	s_waitcnt lgkmcnt(0)
	s_setprio 1
	v_mfma_f32_16x16x32_bf16 v[62:65], v[82:85], v[176:179], v[62:65]
	v_mfma_f32_16x16x32_bf16 v[58:61], v[90:93], v[176:179], v[58:61]
	v_mfma_f32_16x16x32_bf16 v[46:49], v[82:85], v[184:187], v[46:49]
	v_mfma_f32_16x16x32_bf16 v[42:45], v[90:93], v[184:187], v[42:45]
	v_mfma_f32_16x16x32_bf16 v[30:33], v[82:85], v[214:217], v[30:33]
	v_mfma_f32_16x16x32_bf16 v[26:29], v[90:93], v[214:217], v[26:29]
	v_mfma_f32_16x16x32_bf16 v[14:17], v[82:85], v[222:225], v[14:17]
	v_mfma_f32_16x16x32_bf16 v[10:13], v[90:93], v[222:225], v[10:13]
	v_mfma_f32_16x16x32_bf16 v[62:65], v[86:89], v[180:183], v[62:65]
	v_mfma_f32_16x16x32_bf16 v[58:61], v[94:97], v[180:183], v[58:61]
	v_mfma_f32_16x16x32_bf16 v[46:49], v[86:89], v[210:213], v[46:49]
	v_mfma_f32_16x16x32_bf16 v[42:45], v[94:97], v[210:213], v[42:45]
	v_mfma_f32_16x16x32_bf16 v[30:33], v[86:89], v[218:221], v[30:33]
	v_mfma_f32_16x16x32_bf16 v[26:29], v[94:97], v[218:221], v[26:29]
	v_mfma_f32_16x16x32_bf16 v[14:17], v[86:89], v[226:229], v[14:17]
	v_mfma_f32_16x16x32_bf16 v[10:13], v[94:97], v[226:229], v[10:13]
	s_barrier
	s_setprio 0
	s_add_u32 s64, s44, 0x40000
	s_addc_u32 s65, s45, 0
	s_add_i32 s63, s66, s50
	v_lshl_add_u64 v[82:83], s[64:65], 0, v[164:165]
	s_mov_b32 m0, s63
	s_nop 0
	global_load_lds_dwordx4 v[82:83], off
	v_lshl_add_u64 v[82:83], s[64:65], 0, v[168:169]
	s_add_i32 m0, s63, 0x2000
	s_nop 0
	global_load_lds_dwordx4 v[82:83], off
	s_waitcnt vmcnt(6)
	s_barrier
	s_setprio 1
	v_mfma_f32_16x16x32_bf16 v[54:57], v[230:233], v[176:179], v[54:57]
	v_mfma_f32_16x16x32_bf16 v[50:53], v[238:241], v[176:179], v[50:53]
	v_mfma_f32_16x16x32_bf16 v[38:41], v[230:233], v[184:187], v[38:41]
	v_mfma_f32_16x16x32_bf16 v[34:37], v[238:241], v[184:187], v[34:37]
	v_mfma_f32_16x16x32_bf16 v[22:25], v[230:233], v[214:217], v[22:25]
	v_mfma_f32_16x16x32_bf16 v[18:21], v[238:241], v[214:217], v[18:21]
	v_mfma_f32_16x16x32_bf16 v[6:9], v[230:233], v[222:225], v[6:9]
	v_mfma_f32_16x16x32_bf16 v[2:5], v[238:241], v[222:225], v[2:5]
	v_mfma_f32_16x16x32_bf16 v[54:57], v[234:237], v[180:183], v[54:57]
	v_mfma_f32_16x16x32_bf16 v[50:53], v[242:245], v[180:183], v[50:53]
	v_mfma_f32_16x16x32_bf16 v[38:41], v[234:237], v[210:213], v[38:41]
	v_mfma_f32_16x16x32_bf16 v[34:37], v[242:245], v[210:213], v[34:37]
	v_mfma_f32_16x16x32_bf16 v[22:25], v[234:237], v[218:221], v[22:25]
	v_mfma_f32_16x16x32_bf16 v[18:21], v[242:245], v[218:221], v[18:21]
	v_mfma_f32_16x16x32_bf16 v[6:9], v[234:237], v[226:229], v[6:9]
	v_mfma_f32_16x16x32_bf16 v[2:5], v[242:245], v[226:229], v[2:5]
	s_barrier
	s_setprio 0
	s_add_i32 s63, 0, 0x18000
	v_add_u32_e32 v0, s63, v206
	ds_read_b128 v[82:85], v0
	ds_read_b128 v[86:89], v0 offset:1024
	ds_read_b128 v[90:93], v0 offset:2048
	ds_read_b128 v[94:97], v0 offset:3072
	s_add_u32 s46, s46, 0x40000
	s_addc_u32 s47, s47, 0
	s_mov_b32 m0, s53
	v_lshl_add_u64 v[230:231], s[46:47], 0, v[162:163]
	ds_read_b128 v[176:179], v208 offset:32768
	ds_read_b128 v[180:183], v208 offset:33792
	ds_read_b128 v[184:187], v208 offset:34816
	ds_read_b128 v[210:213], v208 offset:35840
	ds_read_b128 v[214:217], v208 offset:36864
	ds_read_b128 v[218:221], v208 offset:37888
	ds_read_b128 v[222:225], v208 offset:38912
	ds_read_b128 v[226:229], v208 offset:39936
	global_load_lds_dwordx4 v[230:231], off
	v_lshl_add_u64 v[230:231], s[46:47], 0, v[166:167]
	s_mov_b32 m0, s54
	s_nop 0
	global_load_lds_dwordx4 v[230:231], off
	s_waitcnt lgkmcnt(8)
	s_barrier
	s_waitcnt lgkmcnt(0)
	s_setprio 1
	v_mfma_f32_16x16x32_bf16 v[142:145], v[82:85], v[176:179], v[142:145]
	v_mfma_f32_16x16x32_bf16 v[138:141], v[90:93], v[176:179], v[138:141]
	v_mfma_f32_16x16x32_bf16 v[126:129], v[82:85], v[184:187], v[126:129]
	v_mfma_f32_16x16x32_bf16 v[122:125], v[90:93], v[184:187], v[122:125]
	v_mfma_f32_16x16x32_bf16 v[110:113], v[82:85], v[214:217], v[110:113]
	v_mfma_f32_16x16x32_bf16 v[106:109], v[90:93], v[214:217], v[106:109]
	v_mfma_f32_16x16x32_bf16 v[78:81], v[82:85], v[222:225], v[78:81]
	v_mfma_f32_16x16x32_bf16 v[74:77], v[90:93], v[222:225], v[74:77]
	v_mfma_f32_16x16x32_bf16 v[142:145], v[86:89], v[180:183], v[142:145]
	v_mfma_f32_16x16x32_bf16 v[138:141], v[94:97], v[180:183], v[138:141]
	v_mfma_f32_16x16x32_bf16 v[126:129], v[86:89], v[210:213], v[126:129]
	v_mfma_f32_16x16x32_bf16 v[122:125], v[94:97], v[210:213], v[122:125]
	v_mfma_f32_16x16x32_bf16 v[110:113], v[86:89], v[218:221], v[110:113]
	v_mfma_f32_16x16x32_bf16 v[106:109], v[94:97], v[218:221], v[106:109]
	v_mfma_f32_16x16x32_bf16 v[78:81], v[86:89], v[226:229], v[78:81]
	v_mfma_f32_16x16x32_bf16 v[74:77], v[94:97], v[226:229], v[74:77]
	s_barrier
	s_setprio 0
	s_add_i32 s46, 0, 0x1c000
	s_add_i32 s47, s63, s50
	v_add_u32_e32 v0, s46, v206
	v_lshl_add_u64 v[246:247], v[246:247], 0, s[94:95]
	s_mov_b32 m0, s47
	ds_read_b128 v[230:233], v0
	ds_read_b128 v[234:237], v0 offset:1024
	ds_read_b128 v[238:241], v0 offset:2048
	ds_read_b128 v[242:245], v0 offset:3072
	global_load_lds_dwordx4 v[246:247], off
	v_lshl_add_u64 v[246:247], v[248:249], 0, s[94:95]
	s_add_i32 m0, s47, 0x2000
	s_nop 0
	global_load_lds_dwordx4 v[246:247], off
	s_barrier
	s_waitcnt lgkmcnt(0)
	s_setprio 1
	v_mfma_f32_16x16x32_bf16 v[134:137], v[230:233], v[176:179], v[134:137]
	v_mfma_f32_16x16x32_bf16 v[130:133], v[238:241], v[176:179], v[130:133]
	v_mfma_f32_16x16x32_bf16 v[118:121], v[230:233], v[184:187], v[118:121]
	v_mfma_f32_16x16x32_bf16 v[114:117], v[238:241], v[184:187], v[114:117]
	v_mfma_f32_16x16x32_bf16 v[102:105], v[230:233], v[214:217], v[102:105]
	v_mfma_f32_16x16x32_bf16 v[98:101], v[238:241], v[214:217], v[98:101]
	v_mfma_f32_16x16x32_bf16 v[70:73], v[230:233], v[222:225], v[70:73]
	v_mfma_f32_16x16x32_bf16 v[66:69], v[238:241], v[222:225], v[66:69]
	v_mfma_f32_16x16x32_bf16 v[134:137], v[234:237], v[180:183], v[134:137]
	v_mfma_f32_16x16x32_bf16 v[130:133], v[242:245], v[180:183], v[130:133]
	v_mfma_f32_16x16x32_bf16 v[118:121], v[234:237], v[210:213], v[118:121]
	v_mfma_f32_16x16x32_bf16 v[114:117], v[242:245], v[210:213], v[114:117]
	v_mfma_f32_16x16x32_bf16 v[102:105], v[234:237], v[218:221], v[102:105]
	v_mfma_f32_16x16x32_bf16 v[98:101], v[242:245], v[218:221], v[98:101]
	v_mfma_f32_16x16x32_bf16 v[70:73], v[234:237], v[226:229], v[70:73]
	v_mfma_f32_16x16x32_bf16 v[66:69], v[242:245], v[226:229], v[66:69]
	s_barrier
	s_setprio 0
	s_mov_b32 m0, s56
	v_lshl_add_u64 v[246:247], v[250:251], 0, s[94:95]
	ds_read_b128 v[176:179], v208 offset:49152
	ds_read_b128 v[180:183], v208 offset:50176
	ds_read_b128 v[184:187], v208 offset:51200
	ds_read_b128 v[210:213], v208 offset:52224
	ds_read_b128 v[214:217], v208 offset:53248
	ds_read_b128 v[218:221], v208 offset:54272
	ds_read_b128 v[222:225], v208 offset:55296
	ds_read_b128 v[226:229], v208 offset:56320
	global_load_lds_dwordx4 v[246:247], off
	v_lshl_add_u64 v[246:247], v[252:253], 0, s[94:95]
	s_mov_b32 m0, s57
	s_nop 0
	global_load_lds_dwordx4 v[246:247], off
	s_barrier
	s_waitcnt lgkmcnt(0)
	s_setprio 1
	v_mfma_f32_16x16x32_bf16 v[62:65], v[82:85], v[176:179], v[62:65]
	v_mfma_f32_16x16x32_bf16 v[58:61], v[90:93], v[176:179], v[58:61]
	v_mfma_f32_16x16x32_bf16 v[46:49], v[82:85], v[184:187], v[46:49]
	v_mfma_f32_16x16x32_bf16 v[42:45], v[90:93], v[184:187], v[42:45]
	v_mfma_f32_16x16x32_bf16 v[30:33], v[82:85], v[214:217], v[30:33]
	v_mfma_f32_16x16x32_bf16 v[26:29], v[90:93], v[214:217], v[26:29]
	v_mfma_f32_16x16x32_bf16 v[14:17], v[82:85], v[222:225], v[14:17]
	v_mfma_f32_16x16x32_bf16 v[10:13], v[90:93], v[222:225], v[10:13]
	v_mfma_f32_16x16x32_bf16 v[62:65], v[86:89], v[180:183], v[62:65]
	v_mfma_f32_16x16x32_bf16 v[58:61], v[94:97], v[180:183], v[58:61]
	v_mfma_f32_16x16x32_bf16 v[46:49], v[86:89], v[210:213], v[46:49]
	v_mfma_f32_16x16x32_bf16 v[42:45], v[94:97], v[210:213], v[42:45]
	v_mfma_f32_16x16x32_bf16 v[30:33], v[86:89], v[218:221], v[30:33]
	v_mfma_f32_16x16x32_bf16 v[26:29], v[94:97], v[218:221], v[26:29]
	v_mfma_f32_16x16x32_bf16 v[14:17], v[86:89], v[226:229], v[14:17]
	v_mfma_f32_16x16x32_bf16 v[10:13], v[94:97], v[226:229], v[10:13]
	s_barrier
	s_setprio 0
	s_add_u32 s44, s44, 0x40080
	s_addc_u32 s45, s45, 0
	s_add_i32 s46, s46, s50
	v_lshl_add_u64 v[82:83], s[44:45], 0, v[164:165]
	s_mov_b32 m0, s46
	s_nop 0
	global_load_lds_dwordx4 v[82:83], off
	v_lshl_add_u64 v[82:83], s[44:45], 0, v[168:169]
	s_add_i32 m0, s46, 0x2000
	s_nop 0
	global_load_lds_dwordx4 v[82:83], off
	s_waitcnt vmcnt(6)
	s_barrier
	s_setprio 1
	v_mfma_f32_16x16x32_bf16 v[54:57], v[230:233], v[176:179], v[54:57]
	v_mfma_f32_16x16x32_bf16 v[50:53], v[238:241], v[176:179], v[50:53]
	v_mfma_f32_16x16x32_bf16 v[38:41], v[230:233], v[184:187], v[38:41]
	v_mfma_f32_16x16x32_bf16 v[34:37], v[238:241], v[184:187], v[34:37]
	v_mfma_f32_16x16x32_bf16 v[22:25], v[230:233], v[214:217], v[22:25]
	v_mfma_f32_16x16x32_bf16 v[18:21], v[238:241], v[214:217], v[18:21]
	v_mfma_f32_16x16x32_bf16 v[6:9], v[230:233], v[222:225], v[6:9]
	v_mfma_f32_16x16x32_bf16 v[2:5], v[238:241], v[222:225], v[2:5]
	v_mfma_f32_16x16x32_bf16 v[54:57], v[234:237], v[180:183], v[54:57]
	v_mfma_f32_16x16x32_bf16 v[50:53], v[242:245], v[180:183], v[50:53]
	v_mfma_f32_16x16x32_bf16 v[38:41], v[234:237], v[210:213], v[38:41]
	v_mfma_f32_16x16x32_bf16 v[34:37], v[242:245], v[210:213], v[34:37]
	v_mfma_f32_16x16x32_bf16 v[22:25], v[234:237], v[218:221], v[22:25]
	v_mfma_f32_16x16x32_bf16 v[18:21], v[242:245], v[218:221], v[18:21]
	v_mfma_f32_16x16x32_bf16 v[6:9], v[234:237], v[226:229], v[6:9]
	v_mfma_f32_16x16x32_bf16 v[2:5], v[242:245], v[226:229], v[2:5]
	s_barrier
	s_setprio 0
	s_add_i32 s62, s62, 2
	s_add_u32 s60, s60, 0x100
	s_addc_u32 s61, s61, 0
	s_add_u32 s42, s42, 0x100
	s_addc_u32 s43, s43, 0
	s_cmp_gt_u32 s62, 13
	s_cbranch_scc0 .LBB0_360
	v_lshl_or_b32 v180, s0, 8, v207
	v_ashrrev_i32_e32 v181, 31, v180
	v_mov_b32_e32 v86, 0
	v_cndmask_b32_e64 v0, 0, 1, s[26:27]
	v_lshl_add_u64 v[176:177], v[180:181], 2, s[22:23]
	v_cmp_ne_u32_e64 s[0:1], 1, v0
	s_andn2_b64 vcc, exec, s[26:27]
	v_mov_b32_e32 v94, 0
	v_mov_b32_e32 v95, v86
	v_mov_b32_e32 v96, 0
	v_mov_b32_e32 v97, 0
	s_cbranch_vccnz .LBB0_363
	global_load_dwordx4 v[94:97], v[176:177], off

.LBB0_586:
	s_add_u32 s22, s20, 0xfffc0080
	s_addc_u32 s23, s21, -1
	s_add_i32 s48, 0, 0x10000
	v_add_u32_e32 v140, s48, v143
	ds_read_b128 v[162:165], v140
	ds_read_b128 v[166:169], v140 offset:1024
	ds_read_b128 v[170:173], v140 offset:2048
	ds_read_b128 v[174:177], v140 offset:3072
	s_cmp_eq_u32 s47, 12
	s_cselect_b32 s25, s9, s23
	s_cselect_b32 s24, s43, s22
	s_cselect_b32 s23, s1, s46
	s_cselect_b32 s22, s44, s45
	v_lshl_add_u64 v[140:141], s[20:21], 0, v[136:137]
	s_add_i32 m0, s3, 0xc000
	ds_read_b128 v[178:181], v145
	ds_read_b128 v[182:185], v145 offset:1024
	ds_read_b128 v[206:209], v145 offset:2048
	ds_read_b128 v[210:213], v145 offset:3072
	ds_read_b128 v[214:217], v145 offset:4096
	ds_read_b128 v[218:221], v145 offset:5120
	ds_read_b128 v[222:225], v145 offset:6144
	ds_read_b128 v[226:229], v145 offset:7168
	global_load_lds_dwordx4 v[140:141], off
	v_lshl_add_u64 v[140:141], s[20:21], 0, v[138:139]
	s_add_i32 m0, s3, 0xe000
	s_nop 0
	global_load_lds_dwordx4 v[140:141], off
	s_waitcnt lgkmcnt(8)
	s_barrier
	s_waitcnt lgkmcnt(0)
	s_setprio 1
	v_mfma_f32_16x16x32_bf16 v[122:125], v[162:165], v[178:181], v[122:125]
	v_mfma_f32_16x16x32_bf16 v[114:117], v[170:173], v[178:181], v[114:117]
	v_mfma_f32_16x16x32_bf16 v[106:109], v[162:165], v[206:209], v[106:109]
	v_mfma_f32_16x16x32_bf16 v[98:101], v[170:173], v[206:209], v[98:101]
	v_mfma_f32_16x16x32_bf16 v[90:93], v[162:165], v[214:217], v[90:93]
	v_mfma_f32_16x16x32_bf16 v[82:85], v[170:173], v[214:217], v[82:85]
	v_mfma_f32_16x16x32_bf16 v[74:77], v[162:165], v[222:225], v[74:77]
	v_mfma_f32_16x16x32_bf16 v[66:69], v[170:173], v[222:225], v[66:69]
	v_mfma_f32_16x16x32_bf16 v[122:125], v[166:169], v[182:185], v[122:125]
	v_mfma_f32_16x16x32_bf16 v[114:117], v[174:177], v[182:185], v[114:117]
	v_mfma_f32_16x16x32_bf16 v[106:109], v[166:169], v[210:213], v[106:109]
	v_mfma_f32_16x16x32_bf16 v[98:101], v[174:177], v[210:213], v[98:101]
	v_mfma_f32_16x16x32_bf16 v[90:93], v[166:169], v[218:221], v[90:93]
	v_mfma_f32_16x16x32_bf16 v[82:85], v[174:177], v[218:221], v[82:85]
	v_mfma_f32_16x16x32_bf16 v[74:77], v[166:169], v[226:229], v[74:77]
	v_mfma_f32_16x16x32_bf16 v[66:69], v[174:177], v[226:229], v[66:69]
	s_barrier
	s_setprio 0
	s_add_i32 s50, 0, 0x14000
	v_add_u32_e32 v140, s50, v143
	s_add_i32 s48, s48, s29
	ds_read_b128 v[230:233], v140
	ds_read_b128 v[234:237], v140 offset:1024
	ds_read_b128 v[238:241], v140 offset:2048
	ds_read_b128 v[242:245], v140 offset:3072
	v_lshl_add_u64 v[140:141], s[22:23], 0, v[0:1]
	s_mov_b32 m0, s48
	v_lshl_add_u64 v[186:187], s[22:23], 0, v[130:131]
	global_load_lds_dwordx4 v[140:141], off
	s_add_i32 m0, s48, 0x2000
	s_nop 0
	global_load_lds_dwordx4 v[186:187], off
	s_barrier
	s_waitcnt lgkmcnt(0)
	s_setprio 1
	v_mfma_f32_16x16x32_bf16 v[126:129], v[230:233], v[178:181], v[126:129]
	v_mfma_f32_16x16x32_bf16 v[118:121], v[238:241], v[178:181], v[118:121]
	v_mfma_f32_16x16x32_bf16 v[110:113], v[230:233], v[206:209], v[110:113]
	v_mfma_f32_16x16x32_bf16 v[102:105], v[238:241], v[206:209], v[102:105]
	v_mfma_f32_16x16x32_bf16 v[94:97], v[230:233], v[214:217], v[94:97]
	v_mfma_f32_16x16x32_bf16 v[86:89], v[238:241], v[214:217], v[86:89]
	v_mfma_f32_16x16x32_bf16 v[78:81], v[230:233], v[222:225], v[78:81]
	v_mfma_f32_16x16x32_bf16 v[70:73], v[238:241], v[222:225], v[70:73]
	v_mfma_f32_16x16x32_bf16 v[126:129], v[234:237], v[182:185], v[126:129]
	v_mfma_f32_16x16x32_bf16 v[118:121], v[242:245], v[182:185], v[118:121]
	v_mfma_f32_16x16x32_bf16 v[110:113], v[234:237], v[210:213], v[110:113]
	v_mfma_f32_16x16x32_bf16 v[102:105], v[242:245], v[210:213], v[102:105]
	v_mfma_f32_16x16x32_bf16 v[94:97], v[234:237], v[218:221], v[94:97]
	v_mfma_f32_16x16x32_bf16 v[86:89], v[242:245], v[218:221], v[86:89]
	v_mfma_f32_16x16x32_bf16 v[78:81], v[234:237], v[226:229], v[78:81]
	v_mfma_f32_16x16x32_bf16 v[70:73], v[242:245], v[226:229], v[70:73]
	s_barrier
	s_setprio 0
	s_mov_b32 m0, s3
	v_lshl_add_u64 v[246:247], s[24:25], 0, v[134:135]
	ds_read_b128 v[178:181], v145 offset:16384
	ds_read_b128 v[182:185], v145 offset:17408
	ds_read_b128 v[206:209], v145 offset:18432
	ds_read_b128 v[210:213], v145 offset:19456
	ds_read_b128 v[214:217], v145 offset:20480
	ds_read_b128 v[218:221], v145 offset:21504
	ds_read_b128 v[222:225], v145 offset:22528
	ds_read_b128 v[226:229], v145 offset:23552
	global_load_lds_dwordx4 v[246:247], off
	v_lshl_add_u64 v[248:249], s[24:25], 0, v[132:133]
	s_mov_b32 m0, s31
	s_nop 0
	global_load_lds_dwordx4 v[248:249], off
	s_barrier
	s_waitcnt lgkmcnt(0)
	s_setprio 1
	v_mfma_f32_16x16x32_bf16 v[58:61], v[162:165], v[178:181], v[58:61]
	v_mfma_f32_16x16x32_bf16 v[50:53], v[170:173], v[178:181], v[50:53]
	v_mfma_f32_16x16x32_bf16 v[42:45], v[162:165], v[206:209], v[42:45]
	v_mfma_f32_16x16x32_bf16 v[34:37], v[170:173], v[206:209], v[34:37]
	v_mfma_f32_16x16x32_bf16 v[26:29], v[162:165], v[214:217], v[26:29]
	v_mfma_f32_16x16x32_bf16 v[18:21], v[170:173], v[214:217], v[18:21]
	v_mfma_f32_16x16x32_bf16 v[10:13], v[162:165], v[222:225], v[10:13]
	v_mfma_f32_16x16x32_bf16 v[6:9], v[170:173], v[222:225], v[6:9]
	v_mfma_f32_16x16x32_bf16 v[58:61], v[166:169], v[182:185], v[58:61]
	v_mfma_f32_16x16x32_bf16 v[50:53], v[174:177], v[182:185], v[50:53]
	v_mfma_f32_16x16x32_bf16 v[42:45], v[166:169], v[210:213], v[42:45]
	v_mfma_f32_16x16x32_bf16 v[34:37], v[174:177], v[210:213], v[34:37]
	v_mfma_f32_16x16x32_bf16 v[26:29], v[166:169], v[218:221], v[26:29]
	v_mfma_f32_16x16x32_bf16 v[18:21], v[174:177], v[218:221], v[18:21]
	v_mfma_f32_16x16x32_bf16 v[10:13], v[166:169], v[226:229], v[10:13]
	v_mfma_f32_16x16x32_bf16 v[6:9], v[174:177], v[226:229], v[6:9]
	s_barrier
	s_setprio 0
	s_add_u32 s48, s22, 0x40000
	s_addc_u32 s49, s23, 0
	s_add_i32 s50, s50, s29
	v_lshl_add_u64 v[162:163], s[48:49], 0, v[0:1]
	s_mov_b32 m0, s50
	s_nop 0
	global_load_lds_dwordx4 v[162:163], off
	v_lshl_add_u64 v[162:163], s[48:49], 0, v[130:131]
	s_add_i32 m0, s50, 0x2000
	s_nop 0
	global_load_lds_dwordx4 v[162:163], off
	s_waitcnt vmcnt(6)
	s_barrier
	s_setprio 1
	v_mfma_f32_16x16x32_bf16 v[62:65], v[230:233], v[178:181], v[62:65]
	v_mfma_f32_16x16x32_bf16 v[54:57], v[238:241], v[178:181], v[54:57]
	v_mfma_f32_16x16x32_bf16 v[46:49], v[230:233], v[206:209], v[46:49]
	v_mfma_f32_16x16x32_bf16 v[38:41], v[238:241], v[206:209], v[38:41]
	v_mfma_f32_16x16x32_bf16 v[30:33], v[230:233], v[214:217], v[30:33]
	v_mfma_f32_16x16x32_bf16 v[22:25], v[238:241], v[214:217], v[22:25]
	v_mfma_f32_16x16x32_bf16 v[14:17], v[230:233], v[222:225], v[14:17]
	v_mfma_f32_16x16x32_bf16 v[2:5], v[238:241], v[222:225], v[2:5]
	v_mfma_f32_16x16x32_bf16 v[62:65], v[234:237], v[182:185], v[62:65]
	v_mfma_f32_16x16x32_bf16 v[54:57], v[242:245], v[182:185], v[54:57]
	v_mfma_f32_16x16x32_bf16 v[46:49], v[234:237], v[210:213], v[46:49]
	v_mfma_f32_16x16x32_bf16 v[38:41], v[242:245], v[210:213], v[38:41]
	v_mfma_f32_16x16x32_bf16 v[30:33], v[234:237], v[218:221], v[30:33]
	v_mfma_f32_16x16x32_bf16 v[22:25], v[242:245], v[218:221], v[22:25]
	v_mfma_f32_16x16x32_bf16 v[14:17], v[234:237], v[226:229], v[14:17]
	v_mfma_f32_16x16x32_bf16 v[2:5], v[242:245], v[226:229], v[2:5]
	s_barrier
	s_setprio 0
	s_add_i32 s48, 0, 0x18000
	v_add_u32_e32 v174, s48, v143
	ds_read_b128 v[162:165], v174
	ds_read_b128 v[166:169], v174 offset:1024
	ds_read_b128 v[170:173], v174 offset:2048
	ds_read_b128 v[174:177], v174 offset:3072
	s_add_u32 s24, s24, 0x40000
	s_addc_u32 s25, s25, 0
	s_mov_b32 m0, s34
	v_lshl_add_u64 v[230:231], s[24:25], 0, v[134:135]
	ds_read_b128 v[178:181], v145 offset:32768
	ds_read_b128 v[182:185], v145 offset:33792
	ds_read_b128 v[206:209], v145 offset:34816
	ds_read_b128 v[210:213], v145 offset:35840
	ds_read_b128 v[214:217], v145 offset:36864
	ds_read_b128 v[218:221], v145 offset:37888
	ds_read_b128 v[222:225], v145 offset:38912
	ds_read_b128 v[226:229], v145 offset:39936
	global_load_lds_dwordx4 v[230:231], off
	v_lshl_add_u64 v[230:231], s[24:25], 0, v[132:133]
	s_mov_b32 m0, s35
	s_nop 0
	global_load_lds_dwordx4 v[230:231], off
	s_waitcnt lgkmcnt(8)
	s_barrier
	s_waitcnt lgkmcnt(0)
	s_setprio 1
	v_mfma_f32_16x16x32_bf16 v[122:125], v[162:165], v[178:181], v[122:125]
	v_mfma_f32_16x16x32_bf16 v[114:117], v[170:173], v[178:181], v[114:117]
	v_mfma_f32_16x16x32_bf16 v[106:109], v[162:165], v[206:209], v[106:109]
	v_mfma_f32_16x16x32_bf16 v[98:101], v[170:173], v[206:209], v[98:101]
	v_mfma_f32_16x16x32_bf16 v[90:93], v[162:165], v[214:217], v[90:93]
	v_mfma_f32_16x16x32_bf16 v[82:85], v[170:173], v[214:217], v[82:85]
	v_mfma_f32_16x16x32_bf16 v[74:77], v[162:165], v[222:225], v[74:77]
	v_mfma_f32_16x16x32_bf16 v[66:69], v[170:173], v[222:225], v[66:69]
	v_mfma_f32_16x16x32_bf16 v[122:125], v[166:169], v[182:185], v[122:125]
	v_mfma_f32_16x16x32_bf16 v[114:117], v[174:177], v[182:185], v[114:117]
	v_mfma_f32_16x16x32_bf16 v[106:109], v[166:169], v[210:213], v[106:109]
	v_mfma_f32_16x16x32_bf16 v[98:101], v[174:177], v[210:213], v[98:101]
	v_mfma_f32_16x16x32_bf16 v[90:93], v[166:169], v[218:221], v[90:93]
	v_mfma_f32_16x16x32_bf16 v[82:85], v[174:177], v[218:221], v[82:85]
	v_mfma_f32_16x16x32_bf16 v[74:77], v[166:169], v[226:229], v[74:77]
	v_mfma_f32_16x16x32_bf16 v[66:69], v[174:177], v[226:229], v[66:69]
	s_barrier
	s_setprio 0
	s_add_i32 s24, 0, 0x1c000
	s_add_i32 s25, s48, s29
	v_add_u32_e32 v205, s24, v143
	v_lshl_add_u64 v[140:141], v[140:141], 0, s[94:95]
	s_mov_b32 m0, s25
	ds_read_b128 v[230:233], v205
	ds_read_b128 v[234:237], v205 offset:1024
	ds_read_b128 v[238:241], v205 offset:2048
	ds_read_b128 v[242:245], v205 offset:3072
	global_load_lds_dwordx4 v[140:141], off
	v_lshl_add_u64 v[140:141], v[186:187], 0, s[94:95]
	s_add_i32 m0, s25, 0x2000
	s_nop 0
	global_load_lds_dwordx4 v[140:141], off
	s_barrier
	s_waitcnt lgkmcnt(0)
	s_setprio 1
	v_mfma_f32_16x16x32_bf16 v[126:129], v[230:233], v[178:181], v[126:129]
	v_mfma_f32_16x16x32_bf16 v[118:121], v[238:241], v[178:181], v[118:121]
	v_mfma_f32_16x16x32_bf16 v[110:113], v[230:233], v[206:209], v[110:113]
	v_mfma_f32_16x16x32_bf16 v[102:105], v[238:241], v[206:209], v[102:105]
	v_mfma_f32_16x16x32_bf16 v[94:97], v[230:233], v[214:217], v[94:97]
	v_mfma_f32_16x16x32_bf16 v[86:89], v[238:241], v[214:217], v[86:89]
	v_mfma_f32_16x16x32_bf16 v[78:81], v[230:233], v[222:225], v[78:81]
	v_mfma_f32_16x16x32_bf16 v[70:73], v[238:241], v[222:225], v[70:73]
	v_mfma_f32_16x16x32_bf16 v[126:129], v[234:237], v[182:185], v[126:129]
	v_mfma_f32_16x16x32_bf16 v[118:121], v[242:245], v[182:185], v[118:121]
	v_mfma_f32_16x16x32_bf16 v[110:113], v[234:237], v[210:213], v[110:113]
	v_mfma_f32_16x16x32_bf16 v[102:105], v[242:245], v[210:213], v[102:105]
	v_mfma_f32_16x16x32_bf16 v[94:97], v[234:237], v[218:221], v[94:97]
	v_mfma_f32_16x16x32_bf16 v[86:89], v[242:245], v[218:221], v[86:89]
	v_mfma_f32_16x16x32_bf16 v[78:81], v[234:237], v[226:229], v[78:81]
	v_mfma_f32_16x16x32_bf16 v[70:73], v[242:245], v[226:229], v[70:73]
	s_barrier
	s_setprio 0
	s_mov_b32 m0, s37
	v_lshl_add_u64 v[140:141], v[246:247], 0, s[94:95]
	ds_read_b128 v[178:181], v145 offset:49152
	ds_read_b128 v[182:185], v145 offset:50176
	ds_read_b128 v[206:209], v145 offset:51200
	ds_read_b128 v[210:213], v145 offset:52224
	ds_read_b128 v[214:217], v145 offset:53248
	ds_read_b128 v[218:221], v145 offset:54272
	ds_read_b128 v[222:225], v145 offset:55296
	ds_read_b128 v[226:229], v145 offset:56320
	global_load_lds_dwordx4 v[140:141], off
	v_lshl_add_u64 v[140:141], v[248:249], 0, s[94:95]
	s_mov_b32 m0, s40
	s_nop 0
	global_load_lds_dwordx4 v[140:141], off
	s_barrier
	s_waitcnt lgkmcnt(0)
	s_setprio 1
	v_mfma_f32_16x16x32_bf16 v[58:61], v[162:165], v[178:181], v[58:61]
	v_mfma_f32_16x16x32_bf16 v[50:53], v[170:173], v[178:181], v[50:53]
	v_mfma_f32_16x16x32_bf16 v[42:45], v[162:165], v[206:209], v[42:45]
	v_mfma_f32_16x16x32_bf16 v[34:37], v[170:173], v[206:209], v[34:37]
	v_mfma_f32_16x16x32_bf16 v[26:29], v[162:165], v[214:217], v[26:29]
	v_mfma_f32_16x16x32_bf16 v[18:21], v[170:173], v[214:217], v[18:21]
	v_mfma_f32_16x16x32_bf16 v[10:13], v[162:165], v[222:225], v[10:13]
	v_mfma_f32_16x16x32_bf16 v[6:9], v[170:173], v[222:225], v[6:9]
	v_mfma_f32_16x16x32_bf16 v[58:61], v[166:169], v[182:185], v[58:61]
	v_mfma_f32_16x16x32_bf16 v[50:53], v[174:177], v[182:185], v[50:53]
	v_mfma_f32_16x16x32_bf16 v[42:45], v[166:169], v[210:213], v[42:45]
	v_mfma_f32_16x16x32_bf16 v[34:37], v[174:177], v[210:213], v[34:37]
	v_mfma_f32_16x16x32_bf16 v[26:29], v[166:169], v[218:221], v[26:29]
	v_mfma_f32_16x16x32_bf16 v[18:21], v[174:177], v[218:221], v[18:21]
	v_mfma_f32_16x16x32_bf16 v[10:13], v[166:169], v[226:229], v[10:13]
	v_mfma_f32_16x16x32_bf16 v[6:9], v[174:177], v[226:229], v[6:9]
	s_barrier
	s_setprio 0
	s_add_u32 s22, s22, 0x40080
	s_addc_u32 s23, s23, 0
	s_add_i32 s24, s24, s29
	v_lshl_add_u64 v[140:141], s[22:23], 0, v[0:1]
	s_mov_b32 m0, s24
	s_nop 0
	global_load_lds_dwordx4 v[140:141], off
	v_lshl_add_u64 v[140:141], s[22:23], 0, v[130:131]
	s_add_i32 m0, s24, 0x2000
	s_nop 0
	global_load_lds_dwordx4 v[140:141], off
	s_waitcnt vmcnt(6)
	s_barrier
	s_setprio 1
	v_mfma_f32_16x16x32_bf16 v[62:65], v[230:233], v[178:181], v[62:65]
	v_mfma_f32_16x16x32_bf16 v[54:57], v[238:241], v[178:181], v[54:57]
	v_mfma_f32_16x16x32_bf16 v[46:49], v[230:233], v[206:209], v[46:49]
	v_mfma_f32_16x16x32_bf16 v[38:41], v[238:241], v[206:209], v[38:41]
	v_mfma_f32_16x16x32_bf16 v[30:33], v[230:233], v[214:217], v[30:33]
	v_mfma_f32_16x16x32_bf16 v[22:25], v[238:241], v[214:217], v[22:25]
	v_mfma_f32_16x16x32_bf16 v[14:17], v[230:233], v[222:225], v[14:17]
	v_mfma_f32_16x16x32_bf16 v[2:5], v[238:241], v[222:225], v[2:5]
	v_mfma_f32_16x16x32_bf16 v[62:65], v[234:237], v[182:185], v[62:65]
	v_mfma_f32_16x16x32_bf16 v[54:57], v[242:245], v[182:185], v[54:57]
	v_mfma_f32_16x16x32_bf16 v[46:49], v[234:237], v[210:213], v[46:49]
	v_mfma_f32_16x16x32_bf16 v[38:41], v[242:245], v[210:213], v[38:41]
	v_mfma_f32_16x16x32_bf16 v[30:33], v[234:237], v[218:221], v[30:33]
	v_mfma_f32_16x16x32_bf16 v[22:25], v[242:245], v[218:221], v[22:25]
	v_mfma_f32_16x16x32_bf16 v[14:17], v[234:237], v[226:229], v[14:17]
	v_mfma_f32_16x16x32_bf16 v[2:5], v[242:245], v[226:229], v[2:5]
	s_barrier
	s_setprio 0
	s_add_i32 s47, s47, 2
	s_add_u32 s20, s20, 0x100
	s_addc_u32 s21, s21, 0
	s_add_u32 s45, s45, 0x100
	s_addc_u32 s46, s46, 0
	s_cmp_gt_u32 s47, 13
	s_cbranch_scc0 .LBB0_586
	v_pk_mul_f32 v[164:165], v[122:123], s[4:5] op_sel_hi:[1,0]
	v_pk_mul_f32 v[122:123], v[122:123], v[126:127]
	v_pk_mul_f32 v[126:127], v[114:115], s[4:5] op_sel_hi:[1,0]
	v_pk_mul_f32 v[114:115], v[114:115], v[118:119]
	v_exp_f32_e32 v126, v126
	v_exp_f32_e32 v127, v127
	v_pk_mul_f32 v[128:129], v[124:125], v[128:129]
	v_pk_mul_f32 v[124:125], v[124:125], s[4:5] op_sel_hi:[1,0]
	v_exp_f32_e32 v164, v164
	v_pk_add_f32 v[126:127], v[126:127], 1.0 op_sel_hi:[1,0]
	v_exp_f32_e32 v165, v165
	v_rcp_f32_e32 v126, v126
	v_rcp_f32_e32 v127, v127
	v_exp_f32_e32 v124, v124
	v_exp_f32_e32 v125, v125
	v_pk_add_f32 v[164:165], v[164:165], 1.0 op_sel_hi:[1,0]
	v_pk_mul_f32 v[118:119], v[126:127], v[114:115]
	v_pk_mul_f32 v[114:115], v[116:117], s[4:5] op_sel_hi:[1,0]
	v_pk_add_f32 v[124:125], v[124:125], 1.0 op_sel_hi:[1,0]
	v_exp_f32_e32 v114, v114
	v_exp_f32_e32 v115, v115
	v_rcp_f32_e32 v164, v164
	v_rcp_f32_e32 v165, v165
	v_rcp_f32_e32 v124, v124
	v_pk_add_f32 v[114:115], v[114:115], 1.0 op_sel_hi:[1,0]
	v_rcp_f32_e32 v125, v125
	v_rcp_f32_e32 v114, v114
	v_rcp_f32_e32 v115, v115
	v_lshl_or_b32 v140, s42, 7, v144
	v_ashrrev_i32_e32 v141, 31, v140
	v_lshl_add_u32 v162, s2, 8, v142
	v_lshl_add_u64 v[140:141], v[140:141], 1, s[14:15]
	v_pk_mul_f32 v[120:121], v[116:117], v[120:121]
	v_pk_mul_f32 v[122:123], v[164:165], v[122:123]
	v_pk_mul_f32 v[124:125], v[124:125], v[128:129]
	v_pk_mul_f32 v[120:121], v[114:115], v[120:121]
	v_mad_i64_i32 v[126:127], s[20:21], v162, s91, v[140:141]
	v_cvt_pk_bf16_f32 v114, v122, v123
	v_cvt_pk_bf16_f32 v115, v124, v125
	v_cvt_pk_bf16_f32 v116, v118, v119
	v_cvt_pk_bf16_f32 v117, v120, v121
	global_store_dwordx4 v[126:127], v[114:117], off
	v_pk_mul_f32 v[112:113], v[108:109], v[112:113]
	v_pk_mul_f32 v[108:109], v[108:109], s[4:5] op_sel_hi:[1,0]
	v_pk_mul_f32 v[114:115], v[106:107], s[4:5] op_sel_hi:[1,0]
	v_pk_mul_f32 v[106:107], v[106:107], v[110:111]
	v_pk_mul_f32 v[110:111], v[98:99], s[4:5] op_sel_hi:[1,0]
	v_pk_mul_f32 v[98:99], v[98:99], v[102:103]
	v_exp_f32_e32 v110, v110
	v_exp_f32_e32 v111, v111
	v_exp_f32_e32 v114, v114
	v_exp_f32_e32 v115, v115
	v_exp_f32_e32 v108, v108
	v_pk_add_f32 v[110:111], v[110:111], 1.0 op_sel_hi:[1,0]
	v_exp_f32_e32 v109, v109
	v_rcp_f32_e32 v110, v110
	v_rcp_f32_e32 v111, v111
	v_pk_add_f32 v[114:115], v[114:115], 1.0 op_sel_hi:[1,0]
	v_pk_add_f32 v[108:109], v[108:109], 1.0 op_sel_hi:[1,0]
	v_rcp_f32_e32 v114, v114
	v_pk_mul_f32 v[102:103], v[110:111], v[98:99]
	v_pk_mul_f32 v[98:99], v[100:101], s[4:5] op_sel_hi:[1,0]
	v_rcp_f32_e32 v115, v115
	v_exp_f32_e32 v98, v98
	v_exp_f32_e32 v99, v99
	v_rcp_f32_e32 v108, v108
	v_rcp_f32_e32 v109, v109
	v_or_b32_e32 v116, 16, v162
	v_pk_add_f32 v[98:99], v[98:99], 1.0 op_sel_hi:[1,0]
	v_pk_mul_f32 v[104:105], v[100:101], v[104:105]
	v_rcp_f32_e32 v98, v98
	v_rcp_f32_e32 v99, v99
	v_pk_mul_f32 v[106:107], v[114:115], v[106:107]
	v_pk_mul_f32 v[108:109], v[108:109], v[112:113]
	v_mad_i64_i32 v[110:111], s[20:21], v116, s91, v[140:141]
	v_pk_mul_f32 v[104:105], v[98:99], v[104:105]
	v_cvt_pk_bf16_f32 v98, v106, v107
	v_cvt_pk_bf16_f32 v99, v108, v109
	v_cvt_pk_bf16_f32 v100, v102, v103
	v_pk_mul_f32 v[96:97], v[92:93], v[96:97]
	v_cvt_pk_bf16_f32 v101, v104, v105
	global_store_dwordx4 v[110:111], v[98:101], off
	v_pk_mul_f32 v[92:93], v[92:93], s[4:5] op_sel_hi:[1,0]
	v_pk_mul_f32 v[88:89], v[84:85], v[88:89]
	v_pk_mul_f32 v[98:99], v[90:91], s[4:5] op_sel_hi:[1,0]
	v_pk_mul_f32 v[90:91], v[90:91], v[94:95]
	v_pk_mul_f32 v[94:95], v[82:83], s[4:5] op_sel_hi:[1,0]
	v_pk_mul_f32 v[82:83], v[82:83], v[86:87]
	v_exp_f32_e32 v94, v94
	v_exp_f32_e32 v95, v95
	v_exp_f32_e32 v98, v98
	v_exp_f32_e32 v99, v99
	v_exp_f32_e32 v92, v92
	v_pk_add_f32 v[94:95], v[94:95], 1.0 op_sel_hi:[1,0]
	v_exp_f32_e32 v93, v93
	v_rcp_f32_e32 v94, v94
	v_rcp_f32_e32 v95, v95
	v_pk_add_f32 v[98:99], v[98:99], 1.0 op_sel_hi:[1,0]
	v_pk_add_f32 v[92:93], v[92:93], 1.0 op_sel_hi:[1,0]
	v_rcp_f32_e32 v98, v98
	v_pk_mul_f32 v[86:87], v[94:95], v[82:83]
	v_pk_mul_f32 v[82:83], v[84:85], s[4:5] op_sel_hi:[1,0]
	v_rcp_f32_e32 v99, v99
	v_exp_f32_e32 v82, v82
	v_exp_f32_e32 v83, v83
	v_rcp_f32_e32 v92, v92
	v_rcp_f32_e32 v93, v93
	v_or_b32_e32 v100, 32, v162
	v_pk_add_f32 v[82:83], v[82:83], 1.0 op_sel_hi:[1,0]
	v_pk_mul_f32 v[90:91], v[98:99], v[90:91]
	v_rcp_f32_e32 v82, v82
	v_rcp_f32_e32 v83, v83
	v_pk_mul_f32 v[92:93], v[92:93], v[96:97]
	v_mad_i64_i32 v[94:95], s[20:21], v100, s91, v[140:141]
	v_pk_mul_f32 v[88:89], v[82:83], v[88:89]
	v_cvt_pk_bf16_f32 v82, v90, v91
	v_cvt_pk_bf16_f32 v83, v92, v93
	v_cvt_pk_bf16_f32 v84, v86, v87
	v_pk_mul_f32 v[80:81], v[76:77], v[80:81]
	v_cvt_pk_bf16_f32 v85, v88, v89
	global_store_dwordx4 v[94:95], v[82:85], off
	v_pk_mul_f32 v[76:77], v[76:77], s[4:5] op_sel_hi:[1,0]
	v_pk_mul_f32 v[72:73], v[68:69], v[72:73]
	v_pk_mul_f32 v[82:83], v[74:75], s[4:5] op_sel_hi:[1,0]
	v_pk_mul_f32 v[74:75], v[74:75], v[78:79]
	v_pk_mul_f32 v[78:79], v[66:67], s[4:5] op_sel_hi:[1,0]
	v_pk_mul_f32 v[66:67], v[66:67], v[70:71]
	v_exp_f32_e32 v78, v78
	v_exp_f32_e32 v79, v79
	v_exp_f32_e32 v82, v82
	v_exp_f32_e32 v83, v83
	v_exp_f32_e32 v76, v76
	v_pk_add_f32 v[78:79], v[78:79], 1.0 op_sel_hi:[1,0]
	v_exp_f32_e32 v77, v77
	v_rcp_f32_e32 v78, v78
	v_rcp_f32_e32 v79, v79
	v_pk_add_f32 v[82:83], v[82:83], 1.0 op_sel_hi:[1,0]
	v_pk_add_f32 v[76:77], v[76:77], 1.0 op_sel_hi:[1,0]
	v_rcp_f32_e32 v82, v82
	v_pk_mul_f32 v[70:71], v[78:79], v[66:67]
	v_pk_mul_f32 v[66:67], v[68:69], s[4:5] op_sel_hi:[1,0]
	v_rcp_f32_e32 v83, v83
	v_exp_f32_e32 v66, v66
	v_exp_f32_e32 v67, v67
	v_rcp_f32_e32 v76, v76
	v_rcp_f32_e32 v77, v77
	v_or_b32_e32 v84, 48, v162
	v_pk_add_f32 v[66:67], v[66:67], 1.0 op_sel_hi:[1,0]
	v_pk_mul_f32 v[74:75], v[82:83], v[74:75]
	v_rcp_f32_e32 v66, v66
	v_rcp_f32_e32 v67, v67
	v_pk_mul_f32 v[76:77], v[76:77], v[80:81]
	v_mad_i64_i32 v[78:79], s[20:21], v84, s91, v[140:141]
	v_pk_mul_f32 v[72:73], v[66:67], v[72:73]
	v_cvt_pk_bf16_f32 v66, v74, v75
	v_cvt_pk_bf16_f32 v67, v76, v77
	v_cvt_pk_bf16_f32 v68, v70, v71
	v_pk_mul_f32 v[64:65], v[60:61], v[64:65]
	v_cvt_pk_bf16_f32 v69, v72, v73
	global_store_dwordx4 v[78:79], v[66:69], off
	v_pk_mul_f32 v[60:61], v[60:61], s[4:5] op_sel_hi:[1,0]
	v_pk_mul_f32 v[56:57], v[52:53], v[56:57]
	v_pk_mul_f32 v[66:67], v[58:59], s[4:5] op_sel_hi:[1,0]
	v_pk_mul_f32 v[58:59], v[58:59], v[62:63]
	v_pk_mul_f32 v[62:63], v[50:51], s[4:5] op_sel_hi:[1,0]
	v_pk_mul_f32 v[50:51], v[50:51], v[54:55]
	v_exp_f32_e32 v62, v62
	v_exp_f32_e32 v63, v63
	v_exp_f32_e32 v66, v66
	v_exp_f32_e32 v67, v67
	v_exp_f32_e32 v60, v60
	v_pk_add_f32 v[62:63], v[62:63], 1.0 op_sel_hi:[1,0]
	v_exp_f32_e32 v61, v61
	v_rcp_f32_e32 v62, v62
	v_rcp_f32_e32 v63, v63
	v_pk_add_f32 v[66:67], v[66:67], 1.0 op_sel_hi:[1,0]
	v_pk_add_f32 v[60:61], v[60:61], 1.0 op_sel_hi:[1,0]
	v_rcp_f32_e32 v66, v66
	v_pk_mul_f32 v[54:55], v[62:63], v[50:51]
	v_pk_mul_f32 v[50:51], v[52:53], s[4:5] op_sel_hi:[1,0]
	v_rcp_f32_e32 v67, v67
	v_exp_f32_e32 v50, v50
	v_exp_f32_e32 v51, v51
	v_rcp_f32_e32 v60, v60
	v_rcp_f32_e32 v61, v61
	v_add_u32_e32 v68, 0x80, v162
	v_pk_add_f32 v[50:51], v[50:51], 1.0 op_sel_hi:[1,0]
	v_pk_mul_f32 v[58:59], v[66:67], v[58:59]
	v_rcp_f32_e32 v50, v50
	v_rcp_f32_e32 v51, v51
	v_pk_mul_f32 v[60:61], v[60:61], v[64:65]
	v_mad_i64_i32 v[62:63], s[20:21], v68, s91, v[140:141]
	v_pk_mul_f32 v[56:57], v[50:51], v[56:57]
	v_cvt_pk_bf16_f32 v50, v58, v59
	v_cvt_pk_bf16_f32 v51, v60, v61
	v_cvt_pk_bf16_f32 v52, v54, v55
	v_pk_mul_f32 v[48:49], v[44:45], v[48:49]
	v_cvt_pk_bf16_f32 v53, v56, v57
	global_store_dwordx4 v[62:63], v[50:53], off
	v_pk_mul_f32 v[44:45], v[44:45], s[4:5] op_sel_hi:[1,0]
	v_pk_mul_f32 v[40:41], v[36:37], v[40:41]
	v_pk_mul_f32 v[50:51], v[42:43], s[4:5] op_sel_hi:[1,0]
	v_pk_mul_f32 v[42:43], v[42:43], v[46:47]
	v_pk_mul_f32 v[46:47], v[34:35], s[4:5] op_sel_hi:[1,0]
	v_pk_mul_f32 v[34:35], v[34:35], v[38:39]
	v_exp_f32_e32 v46, v46
	v_exp_f32_e32 v47, v47
	v_exp_f32_e32 v50, v50
	v_exp_f32_e32 v51, v51
	v_exp_f32_e32 v44, v44
	v_pk_add_f32 v[46:47], v[46:47], 1.0 op_sel_hi:[1,0]
	v_exp_f32_e32 v45, v45
	v_rcp_f32_e32 v46, v46
	v_rcp_f32_e32 v47, v47
	v_pk_add_f32 v[50:51], v[50:51], 1.0 op_sel_hi:[1,0]
	v_pk_add_f32 v[44:45], v[44:45], 1.0 op_sel_hi:[1,0]
	v_rcp_f32_e32 v50, v50
	v_pk_mul_f32 v[38:39], v[46:47], v[34:35]
	v_pk_mul_f32 v[34:35], v[36:37], s[4:5] op_sel_hi:[1,0]
	v_rcp_f32_e32 v51, v51
	v_exp_f32_e32 v34, v34
	v_exp_f32_e32 v35, v35
	v_rcp_f32_e32 v44, v44
	v_rcp_f32_e32 v45, v45
	v_add_u32_e32 v52, 0x90, v162
	v_pk_add_f32 v[34:35], v[34:35], 1.0 op_sel_hi:[1,0]
	v_pk_mul_f32 v[42:43], v[50:51], v[42:43]
	v_rcp_f32_e32 v34, v34
	v_rcp_f32_e32 v35, v35
	v_pk_mul_f32 v[44:45], v[44:45], v[48:49]
	v_mad_i64_i32 v[46:47], s[20:21], v52, s91, v[140:141]
	v_pk_mul_f32 v[40:41], v[34:35], v[40:41]
	v_cvt_pk_bf16_f32 v34, v42, v43
	v_cvt_pk_bf16_f32 v35, v44, v45
	v_cvt_pk_bf16_f32 v36, v38, v39
	v_pk_mul_f32 v[32:33], v[28:29], v[32:33]
	v_cvt_pk_bf16_f32 v37, v40, v41
	global_store_dwordx4 v[46:47], v[34:37], off
	v_pk_mul_f32 v[28:29], v[28:29], s[4:5] op_sel_hi:[1,0]
	v_pk_mul_f32 v[24:25], v[20:21], v[24:25]
	v_pk_mul_f32 v[34:35], v[26:27], s[4:5] op_sel_hi:[1,0]
	v_pk_mul_f32 v[26:27], v[26:27], v[30:31]
	v_pk_mul_f32 v[30:31], v[18:19], s[4:5] op_sel_hi:[1,0]
	v_pk_mul_f32 v[18:19], v[18:19], v[22:23]
	v_exp_f32_e32 v30, v30
	v_exp_f32_e32 v31, v31
	v_exp_f32_e32 v34, v34
	v_exp_f32_e32 v35, v35
	v_exp_f32_e32 v28, v28
	v_pk_add_f32 v[30:31], v[30:31], 1.0 op_sel_hi:[1,0]
	v_exp_f32_e32 v29, v29
	v_rcp_f32_e32 v30, v30
	v_rcp_f32_e32 v31, v31
	v_pk_add_f32 v[34:35], v[34:35], 1.0 op_sel_hi:[1,0]
	v_pk_add_f32 v[28:29], v[28:29], 1.0 op_sel_hi:[1,0]
	v_rcp_f32_e32 v34, v34
	v_pk_mul_f32 v[22:23], v[30:31], v[18:19]
	v_pk_mul_f32 v[18:19], v[20:21], s[4:5] op_sel_hi:[1,0]
	v_rcp_f32_e32 v35, v35
	v_exp_f32_e32 v18, v18
	v_exp_f32_e32 v19, v19
	v_rcp_f32_e32 v28, v28
	v_rcp_f32_e32 v29, v29
	v_add_u32_e32 v36, 0xa0, v162
	v_pk_add_f32 v[18:19], v[18:19], 1.0 op_sel_hi:[1,0]
	v_pk_mul_f32 v[26:27], v[34:35], v[26:27]
	v_rcp_f32_e32 v18, v18
	v_rcp_f32_e32 v19, v19
	v_pk_mul_f32 v[28:29], v[28:29], v[32:33]
	v_mad_i64_i32 v[30:31], s[20:21], v36, s91, v[140:141]
	v_pk_mul_f32 v[24:25], v[18:19], v[24:25]
	v_cvt_pk_bf16_f32 v18, v26, v27
	v_cvt_pk_bf16_f32 v19, v28, v29
	v_cvt_pk_bf16_f32 v20, v22, v23
	v_pk_mul_f32 v[2:3], v[6:7], v[2:3]
	v_cvt_pk_bf16_f32 v21, v24, v25
	global_store_dwordx4 v[30:31], v[18:21], off
	v_pk_mul_f32 v[16:17], v[12:13], v[16:17]
	v_pk_mul_f32 v[12:13], v[12:13], s[4:5] op_sel_hi:[1,0]
	v_pk_mul_f32 v[18:19], v[10:11], s[4:5] op_sel_hi:[1,0]
	v_pk_mul_f32 v[10:11], v[10:11], v[14:15]
	v_pk_mul_f32 v[14:15], v[6:7], s[4:5] op_sel_hi:[1,0]
	v_exp_f32_e32 v18, v18
	v_exp_f32_e32 v14, v14
	v_exp_f32_e32 v15, v15
	v_exp_f32_e32 v19, v19
	v_exp_f32_e32 v12, v12
	v_exp_f32_e32 v13, v13
	v_pk_add_f32 v[14:15], v[14:15], 1.0 op_sel_hi:[1,0]
	v_pk_add_f32 v[18:19], v[18:19], 1.0 op_sel_hi:[1,0]
	v_rcp_f32_e32 v14, v14
	v_rcp_f32_e32 v15, v15
	v_pk_add_f32 v[12:13], v[12:13], 1.0 op_sel_hi:[1,0]
	v_rcp_f32_e32 v18, v18
	v_rcp_f32_e32 v19, v19
	v_pk_mul_f32 v[6:7], v[14:15], v[2:3]
	v_pk_mul_f32 v[2:3], v[8:9], s[4:5] op_sel_hi:[1,0]
	v_rcp_f32_e32 v12, v12
	v_exp_f32_e32 v2, v2
	v_exp_f32_e32 v3, v3
	v_rcp_f32_e32 v13, v13
	v_add_u32_e32 v20, 0xb0, v162
	v_mad_i64_i32 v[14:15], s[20:21], v20, s91, v[140:141]
	v_pk_add_f32 v[2:3], v[2:3], 1.0 op_sel_hi:[1,0]
	v_pk_mul_f32 v[4:5], v[8:9], v[4:5]
	v_rcp_f32_e32 v2, v2
	v_rcp_f32_e32 v3, v3
	s_and_b64 vcc, exec, s[38:39]
	s_mov_b32 s42, s0
	s_mov_b32 s2, s8
	s_mov_b64 s[22:23], s[18:19]
	s_mov_b64 s[20:21], s[16:17]
	v_pk_mul_f32 v[10:11], v[18:19], v[10:11]
	v_pk_mul_f32 v[12:13], v[12:13], v[16:17]
	v_pk_mul_f32 v[8:9], v[2:3], v[4:5]
	v_cvt_pk_bf16_f32 v2, v10, v11
	v_cvt_pk_bf16_f32 v3, v12, v13
	v_cvt_pk_bf16_f32 v4, v6, v7
	s_nop 0
	v_cvt_pk_bf16_f32 v5, v8, v9
	global_store_dwordx4 v[14:15], v[2:5], off
	s_cbranch_vccz .LBB0_579
	s_waitcnt vmcnt(0)
	s_cmpk_gt_u32 s26, 0xff
	s_cbranch_scc1 .LBB0_590
	s_barrier
